# GEMM k-loops: back-to-back s_setprio 0 / s_setprio 1 pairs in the middle of each 32-MFMA cluster removed (24 sites), on top of v71
# speedup vs baseline: 1.0033x; 1.0033x over previous
.LBB0_173:
	s_waitcnt lgkmcnt(0)
	ds_read_b128 v[148:151], v172
	ds_read_b128 v[152:155], v172 offset:1024
	ds_read_b128 v[156:159], v172 offset:2048
	ds_read_b128 v[160:163], v172 offset:3072
	ds_read_b128 v[178:181], v173
	ds_read_b128 v[182:185], v173 offset:1024
	ds_read_b128 v[186:189], v173 offset:2048
	ds_read_b128 v[190:193], v173 offset:3072
	s_add_u32 s7, s80, 0xfffc0080
	s_addc_u32 s24, s81, -1
	s_cmp_eq_u32 s6, 12
	s_cselect_b32 s85, s1, s24
	s_cselect_b32 s84, s75, s7
	s_cselect_b32 s83, s73, s33
	s_cselect_b32 s82, vcc_lo, vcc_hi
	v_lshl_add_u64 v[198:199], s[80:81], 0, v[140:141]
	s_add_i32 m0, s65, 0xc000
	ds_read_b128 v[194:197], v174
	ds_read_b128 v[202:205], v174 offset:1024
	ds_read_b128 v[210:213], v174 offset:2048
	ds_read_b128 v[214:217], v174 offset:3072
	ds_read_b128 v[218:221], v174 offset:4096
	ds_read_b128 v[222:225], v174 offset:5120
	ds_read_b128 v[226:229], v174 offset:6144
	ds_read_b128 v[230:233], v174 offset:7168
	global_load_lds_dwordx4 v[198:199], off
	v_lshl_add_u64 v[198:199], s[80:81], 0, v[142:143]
	s_add_i32 m0, s65, 0xe000
	s_nop 0
	global_load_lds_dwordx4 v[198:199], off
	s_waitcnt vmcnt(8)
	s_waitcnt lgkmcnt(0)
	s_barrier
	s_setprio 1
	s_waitcnt lgkmcnt(0)
	v_mfma_f32_16x16x32_bf16 v[124:127], v[148:151], v[194:197], v[124:127]
	v_mfma_f32_16x16x32_bf16 v[120:123], v[156:159], v[194:197], v[120:123]
	v_mfma_f32_16x16x32_bf16 v[112:115], v[148:151], v[210:213], v[112:115]
	v_mfma_f32_16x16x32_bf16 v[104:107], v[156:159], v[210:213], v[104:107]
	v_mfma_f32_16x16x32_bf16 v[100:103], v[148:151], v[218:221], v[100:103]
	v_mfma_f32_16x16x32_bf16 v[92:95], v[156:159], v[218:221], v[92:95]
	v_mfma_f32_16x16x32_bf16 v[84:87], v[148:151], v[226:229], v[84:87]
	v_mfma_f32_16x16x32_bf16 v[76:79], v[156:159], v[226:229], v[76:79]
	v_mfma_f32_16x16x32_bf16 v[124:127], v[152:155], v[202:205], v[124:127]
	v_mfma_f32_16x16x32_bf16 v[120:123], v[160:163], v[202:205], v[120:123]
	v_mfma_f32_16x16x32_bf16 v[112:115], v[152:155], v[214:217], v[112:115]
	v_mfma_f32_16x16x32_bf16 v[104:107], v[160:163], v[214:217], v[104:107]
	v_mfma_f32_16x16x32_bf16 v[100:103], v[152:155], v[222:225], v[100:103]
	v_mfma_f32_16x16x32_bf16 v[92:95], v[160:163], v[222:225], v[92:95]
	v_mfma_f32_16x16x32_bf16 v[84:87], v[152:155], v[230:233], v[84:87]
	v_mfma_f32_16x16x32_bf16 v[76:79], v[160:163], v[230:233], v[76:79]
	v_mfma_f32_16x16x32_bf16 v[116:119], v[178:181], v[194:197], v[116:119]
	v_mfma_f32_16x16x32_bf16 v[108:111], v[186:189], v[194:197], v[108:111]
	v_mfma_f32_16x16x32_bf16 v[96:99], v[178:181], v[210:213], v[96:99]
	v_mfma_f32_16x16x32_bf16 v[88:91], v[186:189], v[210:213], v[88:91]
	v_mfma_f32_16x16x32_bf16 v[80:83], v[178:181], v[218:221], v[80:83]
	v_mfma_f32_16x16x32_bf16 v[72:75], v[186:189], v[218:221], v[72:75]
	v_mfma_f32_16x16x32_bf16 v[68:71], v[178:181], v[226:229], v[68:71]
	v_mfma_f32_16x16x32_bf16 v[64:67], v[186:189], v[226:229], v[64:67]
	v_mfma_f32_16x16x32_bf16 v[116:119], v[182:185], v[202:205], v[116:119]
	v_mfma_f32_16x16x32_bf16 v[108:111], v[190:193], v[202:205], v[108:111]
	v_mfma_f32_16x16x32_bf16 v[96:99], v[182:185], v[214:217], v[96:99]
	v_mfma_f32_16x16x32_bf16 v[88:91], v[190:193], v[214:217], v[88:91]
	v_mfma_f32_16x16x32_bf16 v[80:83], v[182:185], v[222:225], v[80:83]
	v_mfma_f32_16x16x32_bf16 v[72:75], v[190:193], v[222:225], v[72:75]
	v_mfma_f32_16x16x32_bf16 v[68:71], v[182:185], v[230:233], v[68:71]
	v_mfma_f32_16x16x32_bf16 v[64:67], v[190:193], v[230:233], v[64:67]
	s_setprio 0
	s_barrier
	s_add_i32 s7, s95, s13
	v_lshl_add_u64 v[198:199], s[82:83], 0, v[132:133]
	s_mov_b32 m0, s7
	ds_read_b128 v[194:197], v174 offset:16384
	ds_read_b128 v[202:205], v174 offset:17408
	ds_read_b128 v[210:213], v174 offset:18432
	ds_read_b128 v[214:217], v174 offset:19456
	ds_read_b128 v[218:221], v174 offset:20480
	ds_read_b128 v[222:225], v174 offset:21504
	ds_read_b128 v[226:229], v174 offset:22528
	ds_read_b128 v[230:233], v174 offset:23552
	global_load_lds_dwordx4 v[198:199], off
	s_add_i32 m0, s7, 0x2000
	s_add_u32 s24, s82, 0x40000
	v_lshl_add_u64 v[206:207], s[82:83], 0, v[136:137]
	s_addc_u32 s25, s83, 0
	s_add_i32 s7, s96, s13
	global_load_lds_dwordx4 v[206:207], off
	v_lshl_add_u64 v[234:235], s[24:25], 0, v[132:133]
	s_mov_b32 m0, s7
	v_lshl_add_u64 v[236:237], s[84:85], 0, v[134:135]
	global_load_lds_dwordx4 v[234:235], off
	v_lshl_add_u64 v[234:235], s[24:25], 0, v[136:137]
	s_add_i32 m0, s7, 0x2000
	s_nop 0
	global_load_lds_dwordx4 v[234:235], off
	s_waitcnt vmcnt(6)
	s_waitcnt lgkmcnt(0)
	s_barrier
	s_setprio 1
	s_waitcnt lgkmcnt(0)
	v_mfma_f32_16x16x32_bf16 v[60:63], v[148:151], v[194:197], v[60:63]
	v_mfma_f32_16x16x32_bf16 v[56:59], v[156:159], v[194:197], v[56:59]
	v_mfma_f32_16x16x32_bf16 v[52:55], v[148:151], v[210:213], v[52:55]
	v_mfma_f32_16x16x32_bf16 v[44:47], v[156:159], v[210:213], v[44:47]
	v_mfma_f32_16x16x32_bf16 v[36:39], v[148:151], v[218:221], v[36:39]
	v_mfma_f32_16x16x32_bf16 v[28:31], v[156:159], v[218:221], v[28:31]
	v_mfma_f32_16x16x32_bf16 v[20:23], v[148:151], v[226:229], v[20:23]
	v_mfma_f32_16x16x32_bf16 v[12:15], v[156:159], v[226:229], v[12:15]
	v_mfma_f32_16x16x32_bf16 v[60:63], v[152:155], v[202:205], v[60:63]
	v_mfma_f32_16x16x32_bf16 v[56:59], v[160:163], v[202:205], v[56:59]
	v_mfma_f32_16x16x32_bf16 v[52:55], v[152:155], v[214:217], v[52:55]
	v_mfma_f32_16x16x32_bf16 v[44:47], v[160:163], v[214:217], v[44:47]
	v_mfma_f32_16x16x32_bf16 v[36:39], v[152:155], v[222:225], v[36:39]
	v_mfma_f32_16x16x32_bf16 v[28:31], v[160:163], v[222:225], v[28:31]
	v_mfma_f32_16x16x32_bf16 v[20:23], v[152:155], v[230:233], v[20:23]
	v_mfma_f32_16x16x32_bf16 v[12:15], v[160:163], v[230:233], v[12:15]
	v_mfma_f32_16x16x32_bf16 v[48:51], v[178:181], v[194:197], v[48:51]
	v_mfma_f32_16x16x32_bf16 v[40:43], v[186:189], v[194:197], v[40:43]
	v_mfma_f32_16x16x32_bf16 v[32:35], v[178:181], v[210:213], v[32:35]
	v_mfma_f32_16x16x32_bf16 v[24:27], v[186:189], v[210:213], v[24:27]
	v_mfma_f32_16x16x32_bf16 v[16:19], v[178:181], v[218:221], v[16:19]
	v_mfma_f32_16x16x32_bf16 v[8:11], v[186:189], v[218:221], v[8:11]
	v_mfma_f32_16x16x32_bf16 v[4:7], v[178:181], v[226:229], v[4:7]
	v_mfma_f32_16x16x32_bf16 v[0:3], v[186:189], v[226:229], v[0:3]
	v_mfma_f32_16x16x32_bf16 v[48:51], v[182:185], v[202:205], v[48:51]
	v_mfma_f32_16x16x32_bf16 v[40:43], v[190:193], v[202:205], v[40:43]
	v_mfma_f32_16x16x32_bf16 v[32:35], v[182:185], v[214:217], v[32:35]
	v_mfma_f32_16x16x32_bf16 v[24:27], v[190:193], v[214:217], v[24:27]
	v_mfma_f32_16x16x32_bf16 v[16:19], v[182:185], v[222:225], v[16:19]
	v_mfma_f32_16x16x32_bf16 v[8:11], v[190:193], v[222:225], v[8:11]
	v_mfma_f32_16x16x32_bf16 v[4:7], v[182:185], v[230:233], v[4:7]
	v_mfma_f32_16x16x32_bf16 v[0:3], v[190:193], v[230:233], v[0:3]
	s_setprio 0
	s_barrier
	s_add_i32 s7, 0, 0x18000
	v_add_u32_e32 v138, s7, v169
	s_add_i32 s86, 0, 0x1c000
	ds_read_b128 v[148:151], v138
	ds_read_b128 v[152:155], v138 offset:1024
	ds_read_b128 v[156:159], v138 offset:2048
	ds_read_b128 v[160:163], v138 offset:3072
	v_add_u32_e32 v138, s86, v169
	ds_read_b128 v[178:181], v138
	ds_read_b128 v[182:185], v138 offset:1024
	ds_read_b128 v[186:189], v138 offset:2048
	ds_read_b128 v[190:193], v138 offset:3072
	v_lshl_add_u64 v[234:235], s[84:85], 0, v[130:131]
	s_mov_b32 m0, s65
	s_nop 0
	global_load_lds_dwordx4 v[234:235], off
	s_mov_b32 m0, s69
	s_nop 0
	global_load_lds_dwordx4 v[236:237], off
	s_add_u32 s24, s84, 0x40000
	s_addc_u32 s25, s85, 0
	s_mov_b32 m0, s87
	v_lshl_add_u64 v[238:239], s[24:25], 0, v[130:131]
	ds_read_b128 v[194:197], v174 offset:32768
	ds_read_b128 v[202:205], v174 offset:33792
	ds_read_b128 v[210:213], v174 offset:34816
	ds_read_b128 v[214:217], v174 offset:35840
	ds_read_b128 v[218:221], v174 offset:36864
	ds_read_b128 v[222:225], v174 offset:37888
	ds_read_b128 v[226:229], v174 offset:38912
	ds_read_b128 v[230:233], v174 offset:39936
	global_load_lds_dwordx4 v[238:239], off
	v_lshl_add_u64 v[238:239], s[24:25], 0, v[134:135]
	s_mov_b32 m0, s88
	s_nop 0
	global_load_lds_dwordx4 v[238:239], off
	s_waitcnt vmcnt(8)
	s_waitcnt lgkmcnt(0)
	s_barrier
	s_setprio 1
	s_waitcnt lgkmcnt(0)
	v_mfma_f32_16x16x32_bf16 v[124:127], v[148:151], v[194:197], v[124:127]
	v_mfma_f32_16x16x32_bf16 v[120:123], v[156:159], v[194:197], v[120:123]
	v_mfma_f32_16x16x32_bf16 v[112:115], v[148:151], v[210:213], v[112:115]
	v_mfma_f32_16x16x32_bf16 v[104:107], v[156:159], v[210:213], v[104:107]
	v_mfma_f32_16x16x32_bf16 v[100:103], v[148:151], v[218:221], v[100:103]
	v_mfma_f32_16x16x32_bf16 v[92:95], v[156:159], v[218:221], v[92:95]
	v_mfma_f32_16x16x32_bf16 v[84:87], v[148:151], v[226:229], v[84:87]
	v_mfma_f32_16x16x32_bf16 v[76:79], v[156:159], v[226:229], v[76:79]
	v_mfma_f32_16x16x32_bf16 v[124:127], v[152:155], v[202:205], v[124:127]
	v_mfma_f32_16x16x32_bf16 v[120:123], v[160:163], v[202:205], v[120:123]
	v_mfma_f32_16x16x32_bf16 v[112:115], v[152:155], v[214:217], v[112:115]
	v_mfma_f32_16x16x32_bf16 v[104:107], v[160:163], v[214:217], v[104:107]
	v_mfma_f32_16x16x32_bf16 v[100:103], v[152:155], v[222:225], v[100:103]
	v_mfma_f32_16x16x32_bf16 v[92:95], v[160:163], v[222:225], v[92:95]
	v_mfma_f32_16x16x32_bf16 v[84:87], v[152:155], v[230:233], v[84:87]
	v_mfma_f32_16x16x32_bf16 v[76:79], v[160:163], v[230:233], v[76:79]
	v_mfma_f32_16x16x32_bf16 v[116:119], v[178:181], v[194:197], v[116:119]
	v_mfma_f32_16x16x32_bf16 v[108:111], v[186:189], v[194:197], v[108:111]
	v_mfma_f32_16x16x32_bf16 v[96:99], v[178:181], v[210:213], v[96:99]
	v_mfma_f32_16x16x32_bf16 v[88:91], v[186:189], v[210:213], v[88:91]
	v_mfma_f32_16x16x32_bf16 v[80:83], v[178:181], v[218:221], v[80:83]
	v_mfma_f32_16x16x32_bf16 v[72:75], v[186:189], v[218:221], v[72:75]
	v_mfma_f32_16x16x32_bf16 v[68:71], v[178:181], v[226:229], v[68:71]
	v_mfma_f32_16x16x32_bf16 v[64:67], v[186:189], v[226:229], v[64:67]
	v_mfma_f32_16x16x32_bf16 v[116:119], v[182:185], v[202:205], v[116:119]
	v_mfma_f32_16x16x32_bf16 v[108:111], v[190:193], v[202:205], v[108:111]
	v_mfma_f32_16x16x32_bf16 v[96:99], v[182:185], v[214:217], v[96:99]
	v_mfma_f32_16x16x32_bf16 v[88:91], v[190:193], v[214:217], v[88:91]
	v_mfma_f32_16x16x32_bf16 v[80:83], v[182:185], v[222:225], v[80:83]
	v_mfma_f32_16x16x32_bf16 v[72:75], v[190:193], v[222:225], v[72:75]
	v_mfma_f32_16x16x32_bf16 v[68:71], v[182:185], v[230:233], v[68:71]
	v_mfma_f32_16x16x32_bf16 v[64:67], v[190:193], v[230:233], v[64:67]
	s_setprio 0
	s_barrier
	s_add_i32 s7, s7, s13
	v_lshl_add_u64 v[198:199], v[198:199], 0, s[66:67]
	s_mov_b32 m0, s7
	ds_read_b128 v[194:197], v174 offset:49152
	ds_read_b128 v[202:205], v174 offset:50176
	ds_read_b128 v[210:213], v174 offset:51200
	ds_read_b128 v[214:217], v174 offset:52224
	ds_read_b128 v[218:221], v174 offset:53248
	ds_read_b128 v[222:225], v174 offset:54272
	ds_read_b128 v[226:229], v174 offset:55296
	ds_read_b128 v[230:233], v174 offset:56320
	global_load_lds_dwordx4 v[198:199], off
	s_add_i32 m0, s7, 0x2000
	s_add_u32 s24, s82, 0x40080
	v_lshl_add_u64 v[198:199], v[206:207], 0, s[66:67]
	s_addc_u32 s25, s83, 0
	s_add_i32 s7, s86, s13
	global_load_lds_dwordx4 v[198:199], off
	v_lshl_add_u64 v[198:199], s[24:25], 0, v[132:133]
	s_mov_b32 m0, s7
	s_nop 0
	global_load_lds_dwordx4 v[198:199], off
	v_lshl_add_u64 v[198:199], s[24:25], 0, v[136:137]
	s_add_i32 m0, s7, 0x2000
	s_nop 0
	global_load_lds_dwordx4 v[198:199], off
	v_lshl_add_u64 v[198:199], v[234:235], 0, s[66:67]
	s_mov_b32 m0, s90
	s_nop 0
	global_load_lds_dwordx4 v[198:199], off
	v_lshl_add_u64 v[198:199], v[236:237], 0, s[66:67]
	s_mov_b32 m0, s91
	s_nop 0
	global_load_lds_dwordx4 v[198:199], off
	s_waitcnt vmcnt(6)
	s_waitcnt lgkmcnt(0)
	s_barrier
	s_setprio 1
	s_waitcnt lgkmcnt(0)
	v_mfma_f32_16x16x32_bf16 v[60:63], v[148:151], v[194:197], v[60:63]
	v_mfma_f32_16x16x32_bf16 v[56:59], v[156:159], v[194:197], v[56:59]
	v_mfma_f32_16x16x32_bf16 v[52:55], v[148:151], v[210:213], v[52:55]
	v_mfma_f32_16x16x32_bf16 v[44:47], v[156:159], v[210:213], v[44:47]
	v_mfma_f32_16x16x32_bf16 v[36:39], v[148:151], v[218:221], v[36:39]
	v_mfma_f32_16x16x32_bf16 v[28:31], v[156:159], v[218:221], v[28:31]
	v_mfma_f32_16x16x32_bf16 v[20:23], v[148:151], v[226:229], v[20:23]
	v_mfma_f32_16x16x32_bf16 v[12:15], v[156:159], v[226:229], v[12:15]
	v_mfma_f32_16x16x32_bf16 v[60:63], v[152:155], v[202:205], v[60:63]
	v_mfma_f32_16x16x32_bf16 v[56:59], v[160:163], v[202:205], v[56:59]
	v_mfma_f32_16x16x32_bf16 v[52:55], v[152:155], v[214:217], v[52:55]
	v_mfma_f32_16x16x32_bf16 v[44:47], v[160:163], v[214:217], v[44:47]
	v_mfma_f32_16x16x32_bf16 v[36:39], v[152:155], v[222:225], v[36:39]
	v_mfma_f32_16x16x32_bf16 v[28:31], v[160:163], v[222:225], v[28:31]
	v_mfma_f32_16x16x32_bf16 v[20:23], v[152:155], v[230:233], v[20:23]
	v_mfma_f32_16x16x32_bf16 v[12:15], v[160:163], v[230:233], v[12:15]
	v_mfma_f32_16x16x32_bf16 v[48:51], v[178:181], v[194:197], v[48:51]
	v_mfma_f32_16x16x32_bf16 v[40:43], v[186:189], v[194:197], v[40:43]
	v_mfma_f32_16x16x32_bf16 v[32:35], v[178:181], v[210:213], v[32:35]
	v_mfma_f32_16x16x32_bf16 v[24:27], v[186:189], v[210:213], v[24:27]
	v_mfma_f32_16x16x32_bf16 v[16:19], v[178:181], v[218:221], v[16:19]
	v_mfma_f32_16x16x32_bf16 v[8:11], v[186:189], v[218:221], v[8:11]
	v_mfma_f32_16x16x32_bf16 v[4:7], v[178:181], v[226:229], v[4:7]
	v_mfma_f32_16x16x32_bf16 v[0:3], v[186:189], v[226:229], v[0:3]
	v_mfma_f32_16x16x32_bf16 v[48:51], v[182:185], v[202:205], v[48:51]
	v_mfma_f32_16x16x32_bf16 v[40:43], v[190:193], v[202:205], v[40:43]
	v_mfma_f32_16x16x32_bf16 v[32:35], v[182:185], v[214:217], v[32:35]
	v_mfma_f32_16x16x32_bf16 v[24:27], v[190:193], v[214:217], v[24:27]
	v_mfma_f32_16x16x32_bf16 v[16:19], v[182:185], v[222:225], v[16:19]
	v_mfma_f32_16x16x32_bf16 v[8:11], v[190:193], v[222:225], v[8:11]
	v_mfma_f32_16x16x32_bf16 v[4:7], v[182:185], v[230:233], v[4:7]
	v_mfma_f32_16x16x32_bf16 v[0:3], v[190:193], v[230:233], v[0:3]
	s_setprio 0
	s_barrier
	s_add_i32 s6, s6, 2
	s_add_u32 s80, s80, 0x100
	s_addc_u32 s81, s81, 0
	s_add_u32 vcc_hi, vcc_hi, 0x100
	s_addc_u32 s33, s33, 0
	s_cmp_gt_u32 s6, 13
	s_cbranch_scc0 .LBB0_173
	s_and_b64 vcc, exec, s[70:71]
	s_cbranch_vccnz .LBB0_178
	v_lshl_add_u32 v148, s0, 8, v168
	s_cmp_gt_i32 s68, 3
	s_mov_b64 s[0:1], -1
	s_cbranch_scc1 .LBB0_179

.LBB0_241:
	ds_read_b128 v[154:157], v151
	ds_read_b128 v[158:161], v151 offset:1024
	ds_read_b128 v[168:171], v151 offset:2048
	ds_read_b128 v[172:175], v151 offset:3072
	ds_read_b128 v[178:181], v152
	ds_read_b128 v[182:185], v152 offset:1024
	ds_read_b128 v[186:189], v152 offset:2048
	ds_read_b128 v[190:193], v152 offset:3072
	s_add_u32 s24, s76, 0xfffc0080
	s_addc_u32 s25, s77, -1
	s_cmp_eq_u32 s86, 12
	s_cselect_b32 s81, s69, s25
	s_cselect_b32 s80, s75, s24
	s_cselect_b32 s79, s67, s33
	s_cselect_b32 s78, vcc_lo, vcc_hi
	v_lshl_add_u64 v[162:163], s[76:77], 0, v[140:141]
	s_add_i32 m0, s84, 0xc000
	ds_read_b128 v[194:197], v153
	ds_read_b128 v[202:205], v153 offset:1024
	ds_read_b128 v[210:213], v153 offset:2048
	ds_read_b128 v[214:217], v153 offset:3072
	ds_read_b128 v[218:221], v153 offset:4096
	ds_read_b128 v[222:225], v153 offset:5120
	ds_read_b128 v[226:229], v153 offset:6144
	ds_read_b128 v[230:233], v153 offset:7168
	global_load_lds_dwordx4 v[162:163], off
	v_lshl_add_u64 v[162:163], s[76:77], 0, v[142:143]
	s_add_i32 m0, s84, 0xe000
	s_nop 0
	global_load_lds_dwordx4 v[162:163], off
	s_waitcnt vmcnt(8)
	s_waitcnt lgkmcnt(0)
	s_barrier
	s_setprio 1
	s_waitcnt lgkmcnt(0)
	v_mfma_f32_16x16x32_bf16 v[124:127], v[154:157], v[194:197], v[124:127]
	v_mfma_f32_16x16x32_bf16 v[120:123], v[168:171], v[194:197], v[120:123]
	v_mfma_f32_16x16x32_bf16 v[112:115], v[154:157], v[210:213], v[112:115]
	v_mfma_f32_16x16x32_bf16 v[104:107], v[168:171], v[210:213], v[104:107]
	v_mfma_f32_16x16x32_bf16 v[100:103], v[154:157], v[218:221], v[100:103]
	v_mfma_f32_16x16x32_bf16 v[92:95], v[168:171], v[218:221], v[92:95]
	v_mfma_f32_16x16x32_bf16 v[84:87], v[154:157], v[226:229], v[84:87]
	v_mfma_f32_16x16x32_bf16 v[76:79], v[168:171], v[226:229], v[76:79]
	v_mfma_f32_16x16x32_bf16 v[124:127], v[158:161], v[202:205], v[124:127]
	v_mfma_f32_16x16x32_bf16 v[120:123], v[172:175], v[202:205], v[120:123]
	v_mfma_f32_16x16x32_bf16 v[112:115], v[158:161], v[214:217], v[112:115]
	v_mfma_f32_16x16x32_bf16 v[104:107], v[172:175], v[214:217], v[104:107]
	v_mfma_f32_16x16x32_bf16 v[100:103], v[158:161], v[222:225], v[100:103]
	v_mfma_f32_16x16x32_bf16 v[92:95], v[172:175], v[222:225], v[92:95]
	v_mfma_f32_16x16x32_bf16 v[84:87], v[158:161], v[230:233], v[84:87]
	v_mfma_f32_16x16x32_bf16 v[76:79], v[172:175], v[230:233], v[76:79]
	v_mfma_f32_16x16x32_bf16 v[116:119], v[178:181], v[194:197], v[116:119]
	v_mfma_f32_16x16x32_bf16 v[108:111], v[186:189], v[194:197], v[108:111]
	v_mfma_f32_16x16x32_bf16 v[96:99], v[178:181], v[210:213], v[96:99]
	v_mfma_f32_16x16x32_bf16 v[88:91], v[186:189], v[210:213], v[88:91]
	v_mfma_f32_16x16x32_bf16 v[80:83], v[178:181], v[218:221], v[80:83]
	v_mfma_f32_16x16x32_bf16 v[72:75], v[186:189], v[218:221], v[72:75]
	v_mfma_f32_16x16x32_bf16 v[68:71], v[178:181], v[226:229], v[68:71]
	v_mfma_f32_16x16x32_bf16 v[64:67], v[186:189], v[226:229], v[64:67]
	v_mfma_f32_16x16x32_bf16 v[116:119], v[182:185], v[202:205], v[116:119]
	v_mfma_f32_16x16x32_bf16 v[108:111], v[190:193], v[202:205], v[108:111]
	v_mfma_f32_16x16x32_bf16 v[96:99], v[182:185], v[214:217], v[96:99]
	v_mfma_f32_16x16x32_bf16 v[88:91], v[190:193], v[214:217], v[88:91]
	v_mfma_f32_16x16x32_bf16 v[80:83], v[182:185], v[222:225], v[80:83]
	v_mfma_f32_16x16x32_bf16 v[72:75], v[190:193], v[222:225], v[72:75]
	v_mfma_f32_16x16x32_bf16 v[68:71], v[182:185], v[230:233], v[68:71]
	v_mfma_f32_16x16x32_bf16 v[64:67], v[190:193], v[230:233], v[64:67]
	s_setprio 0
	s_barrier
	s_add_i32 s24, s94, s83
	v_lshl_add_u64 v[162:163], s[78:79], 0, v[132:133]
	s_mov_b32 m0, s24
	ds_read_b128 v[194:197], v153 offset:16384
	ds_read_b128 v[202:205], v153 offset:17408
	ds_read_b128 v[210:213], v153 offset:18432
	ds_read_b128 v[214:217], v153 offset:19456
	ds_read_b128 v[218:221], v153 offset:20480
	ds_read_b128 v[222:225], v153 offset:21504
	ds_read_b128 v[226:229], v153 offset:22528
	ds_read_b128 v[230:233], v153 offset:23552
	global_load_lds_dwordx4 v[162:163], off
	s_add_i32 m0, s24, 0x2000
	s_add_u32 s24, s78, 0x40000
	v_lshl_add_u64 v[198:199], s[78:79], 0, v[136:137]
	s_addc_u32 s25, s79, 0
	s_add_i32 s52, s95, s83
	global_load_lds_dwordx4 v[198:199], off
	v_lshl_add_u64 v[206:207], s[24:25], 0, v[132:133]
	s_mov_b32 m0, s52
	v_lshl_add_u64 v[234:235], s[80:81], 0, v[134:135]
	global_load_lds_dwordx4 v[206:207], off
	v_lshl_add_u64 v[206:207], s[24:25], 0, v[136:137]
	s_add_i32 m0, s52, 0x2000
	s_nop 0
	global_load_lds_dwordx4 v[206:207], off
	s_waitcnt vmcnt(6)
	s_waitcnt lgkmcnt(0)
	s_barrier
	s_setprio 1
	s_waitcnt lgkmcnt(0)
	v_mfma_f32_16x16x32_bf16 v[60:63], v[154:157], v[194:197], v[60:63]
	v_mfma_f32_16x16x32_bf16 v[56:59], v[168:171], v[194:197], v[56:59]
	v_mfma_f32_16x16x32_bf16 v[52:55], v[154:157], v[210:213], v[52:55]
	v_mfma_f32_16x16x32_bf16 v[44:47], v[168:171], v[210:213], v[44:47]
	v_mfma_f32_16x16x32_bf16 v[36:39], v[154:157], v[218:221], v[36:39]
	v_mfma_f32_16x16x32_bf16 v[28:31], v[168:171], v[218:221], v[28:31]
	v_mfma_f32_16x16x32_bf16 v[20:23], v[154:157], v[226:229], v[20:23]
	v_mfma_f32_16x16x32_bf16 v[12:15], v[168:171], v[226:229], v[12:15]
	v_mfma_f32_16x16x32_bf16 v[60:63], v[158:161], v[202:205], v[60:63]
	v_mfma_f32_16x16x32_bf16 v[56:59], v[172:175], v[202:205], v[56:59]
	v_mfma_f32_16x16x32_bf16 v[52:55], v[158:161], v[214:217], v[52:55]
	v_mfma_f32_16x16x32_bf16 v[44:47], v[172:175], v[214:217], v[44:47]
	v_mfma_f32_16x16x32_bf16 v[36:39], v[158:161], v[222:225], v[36:39]
	v_mfma_f32_16x16x32_bf16 v[28:31], v[172:175], v[222:225], v[28:31]
	v_mfma_f32_16x16x32_bf16 v[20:23], v[158:161], v[230:233], v[20:23]
	v_mfma_f32_16x16x32_bf16 v[12:15], v[172:175], v[230:233], v[12:15]
	v_mfma_f32_16x16x32_bf16 v[48:51], v[178:181], v[194:197], v[48:51]
	v_mfma_f32_16x16x32_bf16 v[40:43], v[186:189], v[194:197], v[40:43]
	v_mfma_f32_16x16x32_bf16 v[32:35], v[178:181], v[210:213], v[32:35]
	v_mfma_f32_16x16x32_bf16 v[24:27], v[186:189], v[210:213], v[24:27]
	v_mfma_f32_16x16x32_bf16 v[16:19], v[178:181], v[218:221], v[16:19]
	v_mfma_f32_16x16x32_bf16 v[8:11], v[186:189], v[218:221], v[8:11]
	v_mfma_f32_16x16x32_bf16 v[4:7], v[178:181], v[226:229], v[4:7]
	v_mfma_f32_16x16x32_bf16 v[0:3], v[186:189], v[226:229], v[0:3]
	v_mfma_f32_16x16x32_bf16 v[48:51], v[182:185], v[202:205], v[48:51]
	v_mfma_f32_16x16x32_bf16 v[40:43], v[190:193], v[202:205], v[40:43]
	v_mfma_f32_16x16x32_bf16 v[32:35], v[182:185], v[214:217], v[32:35]
	v_mfma_f32_16x16x32_bf16 v[24:27], v[190:193], v[214:217], v[24:27]
	v_mfma_f32_16x16x32_bf16 v[16:19], v[182:185], v[222:225], v[16:19]
	v_mfma_f32_16x16x32_bf16 v[8:11], v[190:193], v[222:225], v[8:11]
	v_mfma_f32_16x16x32_bf16 v[4:7], v[182:185], v[230:233], v[4:7]
	v_mfma_f32_16x16x32_bf16 v[0:3], v[190:193], v[230:233], v[0:3]
	s_setprio 0
	s_barrier
	s_add_i32 s52, 0, 0x18000
	v_add_u32_e32 v138, s52, v149
	s_add_i32 s53, 0, 0x1c000
	ds_read_b128 v[154:157], v138
	ds_read_b128 v[158:161], v138 offset:1024
	ds_read_b128 v[168:171], v138 offset:2048
	ds_read_b128 v[172:175], v138 offset:3072
	v_add_u32_e32 v138, s53, v149
	ds_read_b128 v[178:181], v138
	ds_read_b128 v[182:185], v138 offset:1024
	ds_read_b128 v[186:189], v138 offset:2048
	ds_read_b128 v[190:193], v138 offset:3072
	v_lshl_add_u64 v[206:207], s[80:81], 0, v[130:131]
	s_mov_b32 m0, s84
	s_nop 0
	global_load_lds_dwordx4 v[206:207], off
	s_mov_b32 m0, s85
	s_nop 0
	global_load_lds_dwordx4 v[234:235], off
	s_add_u32 s24, s80, 0x40000
	s_addc_u32 s25, s81, 0
	s_mov_b32 m0, s87
	v_lshl_add_u64 v[236:237], s[24:25], 0, v[130:131]
	ds_read_b128 v[194:197], v153 offset:32768
	ds_read_b128 v[202:205], v153 offset:33792
	ds_read_b128 v[210:213], v153 offset:34816
	ds_read_b128 v[214:217], v153 offset:35840
	ds_read_b128 v[218:221], v153 offset:36864
	ds_read_b128 v[222:225], v153 offset:37888
	ds_read_b128 v[226:229], v153 offset:38912
	ds_read_b128 v[230:233], v153 offset:39936
	global_load_lds_dwordx4 v[236:237], off
	v_lshl_add_u64 v[236:237], s[24:25], 0, v[134:135]
	s_mov_b32 m0, s88
	s_nop 0
	global_load_lds_dwordx4 v[236:237], off
	s_waitcnt vmcnt(8)
	s_waitcnt lgkmcnt(0)
	s_barrier
	s_setprio 1
	s_waitcnt lgkmcnt(0)
	v_mfma_f32_16x16x32_bf16 v[124:127], v[154:157], v[194:197], v[124:127]
	v_mfma_f32_16x16x32_bf16 v[120:123], v[168:171], v[194:197], v[120:123]
	v_mfma_f32_16x16x32_bf16 v[112:115], v[154:157], v[210:213], v[112:115]
	v_mfma_f32_16x16x32_bf16 v[104:107], v[168:171], v[210:213], v[104:107]
	v_mfma_f32_16x16x32_bf16 v[100:103], v[154:157], v[218:221], v[100:103]
	v_mfma_f32_16x16x32_bf16 v[92:95], v[168:171], v[218:221], v[92:95]
	v_mfma_f32_16x16x32_bf16 v[84:87], v[154:157], v[226:229], v[84:87]
	v_mfma_f32_16x16x32_bf16 v[76:79], v[168:171], v[226:229], v[76:79]
	v_mfma_f32_16x16x32_bf16 v[124:127], v[158:161], v[202:205], v[124:127]
	v_mfma_f32_16x16x32_bf16 v[120:123], v[172:175], v[202:205], v[120:123]
	v_mfma_f32_16x16x32_bf16 v[112:115], v[158:161], v[214:217], v[112:115]
	v_mfma_f32_16x16x32_bf16 v[104:107], v[172:175], v[214:217], v[104:107]
	v_mfma_f32_16x16x32_bf16 v[100:103], v[158:161], v[222:225], v[100:103]
	v_mfma_f32_16x16x32_bf16 v[92:95], v[172:175], v[222:225], v[92:95]
	v_mfma_f32_16x16x32_bf16 v[84:87], v[158:161], v[230:233], v[84:87]
	v_mfma_f32_16x16x32_bf16 v[76:79], v[172:175], v[230:233], v[76:79]
	v_mfma_f32_16x16x32_bf16 v[116:119], v[178:181], v[194:197], v[116:119]
	v_mfma_f32_16x16x32_bf16 v[108:111], v[186:189], v[194:197], v[108:111]
	v_mfma_f32_16x16x32_bf16 v[96:99], v[178:181], v[210:213], v[96:99]
	v_mfma_f32_16x16x32_bf16 v[88:91], v[186:189], v[210:213], v[88:91]
	v_mfma_f32_16x16x32_bf16 v[80:83], v[178:181], v[218:221], v[80:83]
	v_mfma_f32_16x16x32_bf16 v[72:75], v[186:189], v[218:221], v[72:75]
	v_mfma_f32_16x16x32_bf16 v[68:71], v[178:181], v[226:229], v[68:71]
	v_mfma_f32_16x16x32_bf16 v[64:67], v[186:189], v[226:229], v[64:67]
	v_mfma_f32_16x16x32_bf16 v[116:119], v[182:185], v[202:205], v[116:119]
	v_mfma_f32_16x16x32_bf16 v[108:111], v[190:193], v[202:205], v[108:111]
	v_mfma_f32_16x16x32_bf16 v[96:99], v[182:185], v[214:217], v[96:99]
	v_mfma_f32_16x16x32_bf16 v[88:91], v[190:193], v[214:217], v[88:91]
	v_mfma_f32_16x16x32_bf16 v[80:83], v[182:185], v[222:225], v[80:83]
	v_mfma_f32_16x16x32_bf16 v[72:75], v[190:193], v[222:225], v[72:75]
	v_mfma_f32_16x16x32_bf16 v[68:71], v[182:185], v[230:233], v[68:71]
	v_mfma_f32_16x16x32_bf16 v[64:67], v[190:193], v[230:233], v[64:67]
	s_setprio 0
	s_barrier
	s_add_i32 s24, s52, s83
	v_lshl_add_u64 v[162:163], v[162:163], 0, s[26:27]
	s_mov_b32 m0, s24
	ds_read_b128 v[194:197], v153 offset:49152
	ds_read_b128 v[202:205], v153 offset:50176
	ds_read_b128 v[210:213], v153 offset:51200
	ds_read_b128 v[214:217], v153 offset:52224
	ds_read_b128 v[218:221], v153 offset:53248
	ds_read_b128 v[222:225], v153 offset:54272
	ds_read_b128 v[226:229], v153 offset:55296
	ds_read_b128 v[230:233], v153 offset:56320
	global_load_lds_dwordx4 v[162:163], off
	s_add_i32 m0, s24, 0x2000
	s_add_u32 s24, s78, 0x40080
	v_lshl_add_u64 v[162:163], v[198:199], 0, s[26:27]
	s_addc_u32 s25, s79, 0
	s_add_i32 s52, s53, s83
	global_load_lds_dwordx4 v[162:163], off
	v_lshl_add_u64 v[162:163], s[24:25], 0, v[132:133]
	s_mov_b32 m0, s52
	s_nop 0
	global_load_lds_dwordx4 v[162:163], off
	v_lshl_add_u64 v[162:163], s[24:25], 0, v[136:137]
	s_add_i32 m0, s52, 0x2000
	s_nop 0
	global_load_lds_dwordx4 v[162:163], off
	v_lshl_add_u64 v[162:163], v[206:207], 0, s[26:27]
	s_mov_b32 m0, s90
	s_nop 0
	global_load_lds_dwordx4 v[162:163], off
	v_lshl_add_u64 v[162:163], v[234:235], 0, s[26:27]
	s_mov_b32 m0, s91
	s_nop 0
	global_load_lds_dwordx4 v[162:163], off
	s_waitcnt vmcnt(6)
	s_waitcnt lgkmcnt(0)
	s_barrier
	s_setprio 1
	s_waitcnt lgkmcnt(0)
	v_mfma_f32_16x16x32_bf16 v[60:63], v[154:157], v[194:197], v[60:63]
	v_mfma_f32_16x16x32_bf16 v[56:59], v[168:171], v[194:197], v[56:59]
	v_mfma_f32_16x16x32_bf16 v[52:55], v[154:157], v[210:213], v[52:55]
	v_mfma_f32_16x16x32_bf16 v[44:47], v[168:171], v[210:213], v[44:47]
	v_mfma_f32_16x16x32_bf16 v[36:39], v[154:157], v[218:221], v[36:39]
	v_mfma_f32_16x16x32_bf16 v[28:31], v[168:171], v[218:221], v[28:31]
	v_mfma_f32_16x16x32_bf16 v[20:23], v[154:157], v[226:229], v[20:23]
	v_mfma_f32_16x16x32_bf16 v[12:15], v[168:171], v[226:229], v[12:15]
	v_mfma_f32_16x16x32_bf16 v[60:63], v[158:161], v[202:205], v[60:63]
	v_mfma_f32_16x16x32_bf16 v[56:59], v[172:175], v[202:205], v[56:59]
	v_mfma_f32_16x16x32_bf16 v[52:55], v[158:161], v[214:217], v[52:55]
	v_mfma_f32_16x16x32_bf16 v[44:47], v[172:175], v[214:217], v[44:47]
	v_mfma_f32_16x16x32_bf16 v[36:39], v[158:161], v[222:225], v[36:39]
	v_mfma_f32_16x16x32_bf16 v[28:31], v[172:175], v[222:225], v[28:31]
	v_mfma_f32_16x16x32_bf16 v[20:23], v[158:161], v[230:233], v[20:23]
	v_mfma_f32_16x16x32_bf16 v[12:15], v[172:175], v[230:233], v[12:15]
	v_mfma_f32_16x16x32_bf16 v[48:51], v[178:181], v[194:197], v[48:51]
	v_mfma_f32_16x16x32_bf16 v[40:43], v[186:189], v[194:197], v[40:43]
	v_mfma_f32_16x16x32_bf16 v[32:35], v[178:181], v[210:213], v[32:35]
	v_mfma_f32_16x16x32_bf16 v[24:27], v[186:189], v[210:213], v[24:27]
	v_mfma_f32_16x16x32_bf16 v[16:19], v[178:181], v[218:221], v[16:19]
	v_mfma_f32_16x16x32_bf16 v[8:11], v[186:189], v[218:221], v[8:11]
	v_mfma_f32_16x16x32_bf16 v[4:7], v[178:181], v[226:229], v[4:7]
	v_mfma_f32_16x16x32_bf16 v[0:3], v[186:189], v[226:229], v[0:3]
	v_mfma_f32_16x16x32_bf16 v[48:51], v[182:185], v[202:205], v[48:51]
	v_mfma_f32_16x16x32_bf16 v[40:43], v[190:193], v[202:205], v[40:43]
	v_mfma_f32_16x16x32_bf16 v[32:35], v[182:185], v[214:217], v[32:35]
	v_mfma_f32_16x16x32_bf16 v[24:27], v[190:193], v[214:217], v[24:27]
	v_mfma_f32_16x16x32_bf16 v[16:19], v[182:185], v[222:225], v[16:19]
	v_mfma_f32_16x16x32_bf16 v[8:11], v[190:193], v[222:225], v[8:11]
	v_mfma_f32_16x16x32_bf16 v[4:7], v[182:185], v[230:233], v[4:7]
	v_mfma_f32_16x16x32_bf16 v[0:3], v[190:193], v[230:233], v[0:3]
	s_setprio 0
	s_barrier
	s_add_i32 s86, s86, 2
	s_add_u32 s76, s76, 0x100
	s_addc_u32 s77, s77, 0
	s_add_u32 vcc_hi, vcc_hi, 0x100
	s_addc_u32 s33, s33, 0
	s_cmp_gt_u32 s86, 13
	s_cbranch_scc0 .LBB0_241
	s_and_b64 vcc, exec, s[34:35]
	s_cbranch_vccz .LBB0_244
	s_barrier

.LBB0_462:
	v_add_u32_e32 v156, s83, v161
	v_add_u32_e32 v176, s84, v161
	ds_read_b128 v[144:147], v156
	ds_read_b128 v[148:151], v156 offset:1024
	ds_read_b128 v[152:155], v156 offset:2048
	ds_read_b128 v[156:159], v156 offset:3072
	ds_read_b128 v[164:167], v176
	ds_read_b128 v[168:171], v176 offset:1024
	ds_read_b128 v[172:175], v176 offset:2048
	ds_read_b128 v[176:179], v176 offset:3072
	s_add_u32 s58, s70, 0xfffe0080
	s_addc_u32 s59, s71, -1
	s_cmp_eq_u32 s95, 4
	s_cselect_b32 s75, s57, s59
	s_cselect_b32 s74, s91, s58
	s_cselect_b32 s73, s55, s94
	s_cselect_b32 s72, s92, s93
	v_lshl_add_u64 v[216:217], s[70:71], 0, v[136:137]
	s_add_i32 m0, s77, 0xc000
	ds_read_b128 v[180:183], v163
	ds_read_b128 v[184:187], v163 offset:1024
	ds_read_b128 v[188:191], v163 offset:2048
	ds_read_b128 v[192:195], v163 offset:3072
	ds_read_b128 v[196:199], v163 offset:4096
	ds_read_b128 v[200:203], v163 offset:5120
	ds_read_b128 v[204:207], v163 offset:6144
	ds_read_b128 v[212:215], v163 offset:7168
	global_load_lds_dwordx4 v[216:217], off
	v_lshl_add_u64 v[216:217], s[70:71], 0, v[138:139]
	s_add_i32 m0, s77, 0xe000
	s_nop 0
	global_load_lds_dwordx4 v[216:217], off
	s_waitcnt vmcnt(8)
	s_waitcnt lgkmcnt(0)
	s_barrier
	s_setprio 1
	s_waitcnt lgkmcnt(0)
	v_mfma_f32_16x16x32_bf16 v[124:127], v[144:147], v[180:183], v[124:127]
	v_mfma_f32_16x16x32_bf16 v[120:123], v[152:155], v[180:183], v[120:123]
	v_mfma_f32_16x16x32_bf16 v[116:119], v[144:147], v[188:191], v[116:119]
	v_mfma_f32_16x16x32_bf16 v[112:115], v[152:155], v[188:191], v[112:115]
	v_mfma_f32_16x16x32_bf16 v[108:111], v[144:147], v[196:199], v[108:111]
	v_mfma_f32_16x16x32_bf16 v[104:107], v[152:155], v[196:199], v[104:107]
	v_mfma_f32_16x16x32_bf16 v[100:103], v[144:147], v[204:207], v[100:103]
	v_mfma_f32_16x16x32_bf16 v[96:99], v[152:155], v[204:207], v[96:99]
	v_mfma_f32_16x16x32_bf16 v[124:127], v[148:151], v[184:187], v[124:127]
	v_mfma_f32_16x16x32_bf16 v[120:123], v[156:159], v[184:187], v[120:123]
	v_mfma_f32_16x16x32_bf16 v[116:119], v[148:151], v[192:195], v[116:119]
	v_mfma_f32_16x16x32_bf16 v[112:115], v[156:159], v[192:195], v[112:115]
	v_mfma_f32_16x16x32_bf16 v[108:111], v[148:151], v[200:203], v[108:111]
	v_mfma_f32_16x16x32_bf16 v[104:107], v[156:159], v[200:203], v[104:107]
	v_mfma_f32_16x16x32_bf16 v[100:103], v[148:151], v[212:215], v[100:103]
	v_mfma_f32_16x16x32_bf16 v[96:99], v[156:159], v[212:215], v[96:99]
	v_mfma_f32_16x16x32_bf16 v[92:95], v[164:167], v[180:183], v[92:95]
	v_mfma_f32_16x16x32_bf16 v[88:91], v[172:175], v[180:183], v[88:91]
	v_mfma_f32_16x16x32_bf16 v[84:87], v[164:167], v[188:191], v[84:87]
	v_mfma_f32_16x16x32_bf16 v[80:83], v[172:175], v[188:191], v[80:83]
	v_mfma_f32_16x16x32_bf16 v[76:79], v[164:167], v[196:199], v[76:79]
	v_mfma_f32_16x16x32_bf16 v[72:75], v[172:175], v[196:199], v[72:75]
	v_mfma_f32_16x16x32_bf16 v[68:71], v[164:167], v[204:207], v[68:71]
	v_mfma_f32_16x16x32_bf16 v[64:67], v[172:175], v[204:207], v[64:67]
	v_mfma_f32_16x16x32_bf16 v[92:95], v[168:171], v[184:187], v[92:95]
	v_mfma_f32_16x16x32_bf16 v[88:91], v[176:179], v[184:187], v[88:91]
	v_mfma_f32_16x16x32_bf16 v[84:87], v[168:171], v[192:195], v[84:87]
	v_mfma_f32_16x16x32_bf16 v[80:83], v[176:179], v[192:195], v[80:83]
	v_mfma_f32_16x16x32_bf16 v[76:79], v[168:171], v[200:203], v[76:79]
	v_mfma_f32_16x16x32_bf16 v[72:75], v[176:179], v[200:203], v[72:75]
	v_mfma_f32_16x16x32_bf16 v[68:71], v[168:171], v[212:215], v[68:71]
	v_mfma_f32_16x16x32_bf16 v[64:67], v[176:179], v[212:215], v[64:67]
	s_setprio 0
	s_barrier
	s_add_i32 s58, s83, s76
	v_lshl_add_u64 v[216:217], s[72:73], 0, v[130:131]
	s_mov_b32 m0, s58
	ds_read_b128 v[180:183], v163 offset:16384
	ds_read_b128 v[184:187], v163 offset:17408
	ds_read_b128 v[188:191], v163 offset:18432
	ds_read_b128 v[192:195], v163 offset:19456
	ds_read_b128 v[196:199], v163 offset:20480
	ds_read_b128 v[200:203], v163 offset:21504
	ds_read_b128 v[204:207], v163 offset:22528
	ds_read_b128 v[212:215], v163 offset:23552
	global_load_lds_dwordx4 v[216:217], off
	s_add_i32 m0, s58, 0x2000
	s_add_u32 s96, s72, 0x20000
	v_lshl_add_u64 v[218:219], s[72:73], 0, v[134:135]
	s_addc_u32 s97, s73, 0
	s_add_i32 s58, s84, s76
	global_load_lds_dwordx4 v[218:219], off
	v_lshl_add_u64 v[220:221], s[96:97], 0, v[130:131]
	s_mov_b32 m0, s58
	v_lshl_add_u64 v[222:223], s[74:75], 0, v[132:133]
	global_load_lds_dwordx4 v[220:221], off
	v_lshl_add_u64 v[220:221], s[96:97], 0, v[134:135]
	s_add_i32 m0, s58, 0x2000
	s_nop 0
	global_load_lds_dwordx4 v[220:221], off
	s_waitcnt vmcnt(6)
	s_waitcnt lgkmcnt(0)
	s_barrier
	s_setprio 1
	s_waitcnt lgkmcnt(0)
	v_mfma_f32_16x16x32_bf16 v[60:63], v[144:147], v[180:183], v[60:63]
	v_mfma_f32_16x16x32_bf16 v[56:59], v[152:155], v[180:183], v[56:59]
	v_mfma_f32_16x16x32_bf16 v[52:55], v[144:147], v[188:191], v[52:55]
	v_mfma_f32_16x16x32_bf16 v[48:51], v[152:155], v[188:191], v[48:51]
	v_mfma_f32_16x16x32_bf16 v[44:47], v[144:147], v[196:199], v[44:47]
	v_mfma_f32_16x16x32_bf16 v[40:43], v[152:155], v[196:199], v[40:43]
	v_mfma_f32_16x16x32_bf16 v[36:39], v[144:147], v[204:207], v[36:39]
	v_mfma_f32_16x16x32_bf16 v[32:35], v[152:155], v[204:207], v[32:35]
	v_mfma_f32_16x16x32_bf16 v[60:63], v[148:151], v[184:187], v[60:63]
	v_mfma_f32_16x16x32_bf16 v[56:59], v[156:159], v[184:187], v[56:59]
	v_mfma_f32_16x16x32_bf16 v[52:55], v[148:151], v[192:195], v[52:55]
	v_mfma_f32_16x16x32_bf16 v[48:51], v[156:159], v[192:195], v[48:51]
	v_mfma_f32_16x16x32_bf16 v[44:47], v[148:151], v[200:203], v[44:47]
	v_mfma_f32_16x16x32_bf16 v[40:43], v[156:159], v[200:203], v[40:43]
	v_mfma_f32_16x16x32_bf16 v[36:39], v[148:151], v[212:215], v[36:39]
	v_mfma_f32_16x16x32_bf16 v[32:35], v[156:159], v[212:215], v[32:35]
	v_mfma_f32_16x16x32_bf16 v[28:31], v[164:167], v[180:183], v[28:31]
	v_mfma_f32_16x16x32_bf16 v[24:27], v[172:175], v[180:183], v[24:27]
	v_mfma_f32_16x16x32_bf16 v[20:23], v[164:167], v[188:191], v[20:23]
	v_mfma_f32_16x16x32_bf16 v[16:19], v[172:175], v[188:191], v[16:19]
	v_mfma_f32_16x16x32_bf16 v[12:15], v[164:167], v[196:199], v[12:15]
	v_mfma_f32_16x16x32_bf16 v[8:11], v[172:175], v[196:199], v[8:11]
	v_mfma_f32_16x16x32_bf16 v[4:7], v[164:167], v[204:207], v[4:7]
	v_mfma_f32_16x16x32_bf16 v[0:3], v[172:175], v[204:207], v[0:3]
	v_mfma_f32_16x16x32_bf16 v[28:31], v[168:171], v[184:187], v[28:31]
	v_mfma_f32_16x16x32_bf16 v[24:27], v[176:179], v[184:187], v[24:27]
	v_mfma_f32_16x16x32_bf16 v[20:23], v[168:171], v[192:195], v[20:23]
	v_mfma_f32_16x16x32_bf16 v[16:19], v[176:179], v[192:195], v[16:19]
	v_mfma_f32_16x16x32_bf16 v[12:15], v[168:171], v[200:203], v[12:15]
	v_mfma_f32_16x16x32_bf16 v[8:11], v[176:179], v[200:203], v[8:11]
	v_mfma_f32_16x16x32_bf16 v[4:7], v[168:171], v[212:215], v[4:7]
	v_mfma_f32_16x16x32_bf16 v[0:3], v[176:179], v[212:215], v[0:3]
	s_setprio 0
	s_barrier
	s_add_i32 s58, 0, 0x18000
	s_add_i32 s59, 0, 0x1c000
	v_add_u32_e32 v156, s58, v161
	v_add_u32_e32 v176, s59, v161
	ds_read_b128 v[144:147], v156
	ds_read_b128 v[148:151], v156 offset:1024
	ds_read_b128 v[152:155], v156 offset:2048
	ds_read_b128 v[156:159], v156 offset:3072
	ds_read_b128 v[164:167], v176
	ds_read_b128 v[168:171], v176 offset:1024
	ds_read_b128 v[172:175], v176 offset:2048
	ds_read_b128 v[176:179], v176 offset:3072
	v_lshl_add_u64 v[220:221], s[74:75], 0, v[128:129]
	s_mov_b32 m0, s77
	s_nop 0
	global_load_lds_dwordx4 v[220:221], off
	s_mov_b32 m0, s78
	s_nop 0
	global_load_lds_dwordx4 v[222:223], off
	s_add_u32 s74, s74, 0x20000
	s_addc_u32 s75, s75, 0
	s_mov_b32 m0, s79
	v_lshl_add_u64 v[224:225], s[74:75], 0, v[128:129]
	ds_read_b128 v[180:183], v163 offset:32768
	ds_read_b128 v[184:187], v163 offset:33792
	ds_read_b128 v[188:191], v163 offset:34816
	ds_read_b128 v[192:195], v163 offset:35840
	ds_read_b128 v[196:199], v163 offset:36864
	ds_read_b128 v[200:203], v163 offset:37888
	ds_read_b128 v[204:207], v163 offset:38912
	ds_read_b128 v[212:215], v163 offset:39936
	global_load_lds_dwordx4 v[224:225], off
	v_lshl_add_u64 v[224:225], s[74:75], 0, v[132:133]
	s_mov_b32 m0, s80
	s_nop 0
	global_load_lds_dwordx4 v[224:225], off
	s_waitcnt vmcnt(8)
	s_waitcnt lgkmcnt(0)
	s_barrier
	s_setprio 1
	s_waitcnt lgkmcnt(0)
	v_mfma_f32_16x16x32_bf16 v[124:127], v[144:147], v[180:183], v[124:127]
	v_mfma_f32_16x16x32_bf16 v[120:123], v[152:155], v[180:183], v[120:123]
	v_mfma_f32_16x16x32_bf16 v[116:119], v[144:147], v[188:191], v[116:119]
	v_mfma_f32_16x16x32_bf16 v[112:115], v[152:155], v[188:191], v[112:115]
	v_mfma_f32_16x16x32_bf16 v[108:111], v[144:147], v[196:199], v[108:111]
	v_mfma_f32_16x16x32_bf16 v[104:107], v[152:155], v[196:199], v[104:107]
	v_mfma_f32_16x16x32_bf16 v[100:103], v[144:147], v[204:207], v[100:103]
	v_mfma_f32_16x16x32_bf16 v[96:99], v[152:155], v[204:207], v[96:99]
	v_mfma_f32_16x16x32_bf16 v[124:127], v[148:151], v[184:187], v[124:127]
	v_mfma_f32_16x16x32_bf16 v[120:123], v[156:159], v[184:187], v[120:123]
	v_mfma_f32_16x16x32_bf16 v[116:119], v[148:151], v[192:195], v[116:119]
	v_mfma_f32_16x16x32_bf16 v[112:115], v[156:159], v[192:195], v[112:115]
	v_mfma_f32_16x16x32_bf16 v[108:111], v[148:151], v[200:203], v[108:111]
	v_mfma_f32_16x16x32_bf16 v[104:107], v[156:159], v[200:203], v[104:107]
	v_mfma_f32_16x16x32_bf16 v[100:103], v[148:151], v[212:215], v[100:103]
	v_mfma_f32_16x16x32_bf16 v[96:99], v[156:159], v[212:215], v[96:99]
	v_mfma_f32_16x16x32_bf16 v[92:95], v[164:167], v[180:183], v[92:95]
	v_mfma_f32_16x16x32_bf16 v[88:91], v[172:175], v[180:183], v[88:91]
	v_mfma_f32_16x16x32_bf16 v[84:87], v[164:167], v[188:191], v[84:87]
	v_mfma_f32_16x16x32_bf16 v[80:83], v[172:175], v[188:191], v[80:83]
	v_mfma_f32_16x16x32_bf16 v[76:79], v[164:167], v[196:199], v[76:79]
	v_mfma_f32_16x16x32_bf16 v[72:75], v[172:175], v[196:199], v[72:75]
	v_mfma_f32_16x16x32_bf16 v[68:71], v[164:167], v[204:207], v[68:71]
	v_mfma_f32_16x16x32_bf16 v[64:67], v[172:175], v[204:207], v[64:67]
	v_mfma_f32_16x16x32_bf16 v[92:95], v[168:171], v[184:187], v[92:95]
	v_mfma_f32_16x16x32_bf16 v[88:91], v[176:179], v[184:187], v[88:91]
	v_mfma_f32_16x16x32_bf16 v[84:87], v[168:171], v[192:195], v[84:87]
	v_mfma_f32_16x16x32_bf16 v[80:83], v[176:179], v[192:195], v[80:83]
	v_mfma_f32_16x16x32_bf16 v[76:79], v[168:171], v[200:203], v[76:79]
	v_mfma_f32_16x16x32_bf16 v[72:75], v[176:179], v[200:203], v[72:75]
	v_mfma_f32_16x16x32_bf16 v[68:71], v[168:171], v[212:215], v[68:71]
	v_mfma_f32_16x16x32_bf16 v[64:67], v[176:179], v[212:215], v[64:67]
	s_setprio 0
	s_barrier
	s_add_i32 s58, s58, s76
	v_lshl_add_u64 v[216:217], v[216:217], 0, s[38:39]
	s_mov_b32 m0, s58
	ds_read_b128 v[180:183], v163 offset:49152
	ds_read_b128 v[184:187], v163 offset:50176
	ds_read_b128 v[188:191], v163 offset:51200
	ds_read_b128 v[192:195], v163 offset:52224
	ds_read_b128 v[196:199], v163 offset:53248
	ds_read_b128 v[200:203], v163 offset:54272
	ds_read_b128 v[204:207], v163 offset:55296
	ds_read_b128 v[212:215], v163 offset:56320
	global_load_lds_dwordx4 v[216:217], off
	s_add_i32 m0, s58, 0x2000
	s_add_u32 s72, s72, 0x20080
	v_lshl_add_u64 v[216:217], v[218:219], 0, s[38:39]
	s_addc_u32 s73, s73, 0
	s_add_i32 s58, s59, s76
	global_load_lds_dwordx4 v[216:217], off
	v_lshl_add_u64 v[216:217], s[72:73], 0, v[130:131]
	s_mov_b32 m0, s58
	s_nop 0
	global_load_lds_dwordx4 v[216:217], off
	v_lshl_add_u64 v[216:217], s[72:73], 0, v[134:135]
	s_add_i32 m0, s58, 0x2000
	s_nop 0
	global_load_lds_dwordx4 v[216:217], off
	v_lshl_add_u64 v[216:217], v[220:221], 0, s[38:39]
	s_mov_b32 m0, s81
	s_nop 0
	global_load_lds_dwordx4 v[216:217], off
	v_lshl_add_u64 v[216:217], v[222:223], 0, s[38:39]
	s_mov_b32 m0, s82
	s_nop 0
	global_load_lds_dwordx4 v[216:217], off
	s_waitcnt vmcnt(6)
	s_waitcnt lgkmcnt(0)
	s_barrier
	s_setprio 1
	s_waitcnt lgkmcnt(0)
	v_mfma_f32_16x16x32_bf16 v[60:63], v[144:147], v[180:183], v[60:63]
	v_mfma_f32_16x16x32_bf16 v[56:59], v[152:155], v[180:183], v[56:59]
	v_mfma_f32_16x16x32_bf16 v[52:55], v[144:147], v[188:191], v[52:55]
	v_mfma_f32_16x16x32_bf16 v[48:51], v[152:155], v[188:191], v[48:51]
	v_mfma_f32_16x16x32_bf16 v[44:47], v[144:147], v[196:199], v[44:47]
	v_mfma_f32_16x16x32_bf16 v[40:43], v[152:155], v[196:199], v[40:43]
	v_mfma_f32_16x16x32_bf16 v[36:39], v[144:147], v[204:207], v[36:39]
	v_mfma_f32_16x16x32_bf16 v[32:35], v[152:155], v[204:207], v[32:35]
	v_mfma_f32_16x16x32_bf16 v[60:63], v[148:151], v[184:187], v[60:63]
	v_mfma_f32_16x16x32_bf16 v[56:59], v[156:159], v[184:187], v[56:59]
	v_mfma_f32_16x16x32_bf16 v[52:55], v[148:151], v[192:195], v[52:55]
	v_mfma_f32_16x16x32_bf16 v[48:51], v[156:159], v[192:195], v[48:51]
	v_mfma_f32_16x16x32_bf16 v[44:47], v[148:151], v[200:203], v[44:47]
	v_mfma_f32_16x16x32_bf16 v[40:43], v[156:159], v[200:203], v[40:43]
	v_mfma_f32_16x16x32_bf16 v[36:39], v[148:151], v[212:215], v[36:39]
	v_mfma_f32_16x16x32_bf16 v[32:35], v[156:159], v[212:215], v[32:35]
	v_mfma_f32_16x16x32_bf16 v[28:31], v[164:167], v[180:183], v[28:31]
	v_mfma_f32_16x16x32_bf16 v[24:27], v[172:175], v[180:183], v[24:27]
	v_mfma_f32_16x16x32_bf16 v[20:23], v[164:167], v[188:191], v[20:23]
	v_mfma_f32_16x16x32_bf16 v[16:19], v[172:175], v[188:191], v[16:19]
	v_mfma_f32_16x16x32_bf16 v[12:15], v[164:167], v[196:199], v[12:15]
	v_mfma_f32_16x16x32_bf16 v[8:11], v[172:175], v[196:199], v[8:11]
	v_mfma_f32_16x16x32_bf16 v[4:7], v[164:167], v[204:207], v[4:7]
	v_mfma_f32_16x16x32_bf16 v[0:3], v[172:175], v[204:207], v[0:3]
	v_mfma_f32_16x16x32_bf16 v[28:31], v[168:171], v[184:187], v[28:31]
	v_mfma_f32_16x16x32_bf16 v[24:27], v[176:179], v[184:187], v[24:27]
	v_mfma_f32_16x16x32_bf16 v[20:23], v[168:171], v[192:195], v[20:23]
	v_mfma_f32_16x16x32_bf16 v[16:19], v[176:179], v[192:195], v[16:19]
	v_mfma_f32_16x16x32_bf16 v[12:15], v[168:171], v[200:203], v[12:15]
	v_mfma_f32_16x16x32_bf16 v[8:11], v[176:179], v[200:203], v[8:11]
	v_mfma_f32_16x16x32_bf16 v[4:7], v[168:171], v[212:215], v[4:7]
	v_mfma_f32_16x16x32_bf16 v[0:3], v[176:179], v[212:215], v[0:3]
	s_setprio 0
	s_barrier
	s_add_i32 s95, s95, 2
	s_add_u32 s70, s70, 0x100
	s_addc_u32 s71, s71, 0
	s_add_u32 s93, s93, 0x100
	s_addc_u32 s94, s94, 0
	s_cmp_gt_u32 s95, 5
	s_cbranch_scc0 .LBB0_462
	s_and_b64 vcc, exec, s[40:41]
	s_cbranch_vccz .LBB0_465
	s_barrier

.LBB0_544:
	ds_read_b128 v[100:103], v199
	ds_read_b128 v[108:111], v199 offset:1024
	ds_read_b128 v[112:115], v199 offset:2048
	ds_read_b128 v[116:119], v199 offset:3072
	ds_read_b128 v[156:159], v200
	ds_read_b128 v[160:163], v200 offset:1024
	ds_read_b128 v[164:167], v200 offset:2048
	ds_read_b128 v[168:171], v200 offset:3072
	s_add_u32 s56, s54, 0xfffc0080
	s_addc_u32 s57, s55, -1
	s_cmp_eq_u32 s88, 12
	s_cselect_b32 s65, s43, s57
	s_cselect_b32 s64, s49, s56
	s_cselect_b32 s57, s41, s33
	s_cselect_b32 s56, s53, s87
	v_lshl_add_u64 v[216:217], s[54:55], 0, v[148:149]
	s_add_i32 m0, s67, 0xc000
	ds_read_b128 v[172:175], v201
	ds_read_b128 v[176:179], v201 offset:1024
	ds_read_b128 v[180:183], v201 offset:2048
	ds_read_b128 v[184:187], v201 offset:3072
	ds_read_b128 v[188:191], v201 offset:4096
	ds_read_b128 v[192:195], v201 offset:5120
	ds_read_b128 v[204:207], v201 offset:6144
	ds_read_b128 v[212:215], v201 offset:7168
	global_load_lds_dwordx4 v[216:217], off
	v_lshl_add_u64 v[216:217], s[54:55], 0, v[150:151]
	s_add_i32 m0, s67, 0xe000
	s_nop 0
	global_load_lds_dwordx4 v[216:217], off
	s_waitcnt vmcnt(8)
	s_waitcnt lgkmcnt(0)
	s_barrier
	s_setprio 1
	s_waitcnt lgkmcnt(0)
	v_mfma_f32_16x16x32_bf16 v[140:143], v[100:103], v[172:175], v[140:143]
	v_mfma_f32_16x16x32_bf16 v[136:139], v[112:115], v[172:175], v[136:139]
	v_mfma_f32_16x16x32_bf16 v[124:127], v[100:103], v[180:183], v[124:127]
	v_mfma_f32_16x16x32_bf16 v[120:123], v[112:115], v[180:183], v[120:123]
	v_mfma_f32_16x16x32_bf16 v[92:95], v[100:103], v[188:191], v[92:95]
	v_mfma_f32_16x16x32_bf16 v[88:91], v[112:115], v[188:191], v[88:91]
	v_mfma_f32_16x16x32_bf16 v[76:79], v[100:103], v[204:207], v[76:79]
	v_mfma_f32_16x16x32_bf16 v[72:75], v[112:115], v[204:207], v[72:75]
	v_mfma_f32_16x16x32_bf16 v[140:143], v[108:111], v[176:179], v[140:143]
	v_mfma_f32_16x16x32_bf16 v[136:139], v[116:119], v[176:179], v[136:139]
	v_mfma_f32_16x16x32_bf16 v[124:127], v[108:111], v[184:187], v[124:127]
	v_mfma_f32_16x16x32_bf16 v[120:123], v[116:119], v[184:187], v[120:123]
	v_mfma_f32_16x16x32_bf16 v[92:95], v[108:111], v[192:195], v[92:95]
	v_mfma_f32_16x16x32_bf16 v[88:91], v[116:119], v[192:195], v[88:91]
	v_mfma_f32_16x16x32_bf16 v[76:79], v[108:111], v[212:215], v[76:79]
	v_mfma_f32_16x16x32_bf16 v[72:75], v[116:119], v[212:215], v[72:75]
	v_mfma_f32_16x16x32_bf16 v[132:135], v[156:159], v[172:175], v[132:135]
	v_mfma_f32_16x16x32_bf16 v[128:131], v[164:167], v[172:175], v[128:131]
	v_mfma_f32_16x16x32_bf16 v[104:107], v[156:159], v[180:183], v[104:107]
	v_mfma_f32_16x16x32_bf16 v[96:99], v[164:167], v[180:183], v[96:99]
	v_mfma_f32_16x16x32_bf16 v[84:87], v[156:159], v[188:191], v[84:87]
	v_mfma_f32_16x16x32_bf16 v[80:83], v[164:167], v[188:191], v[80:83]
	v_mfma_f32_16x16x32_bf16 v[68:71], v[156:159], v[204:207], v[68:71]
	v_mfma_f32_16x16x32_bf16 v[64:67], v[164:167], v[204:207], v[64:67]
	v_mfma_f32_16x16x32_bf16 v[132:135], v[160:163], v[176:179], v[132:135]
	v_mfma_f32_16x16x32_bf16 v[128:131], v[168:171], v[176:179], v[128:131]
	v_mfma_f32_16x16x32_bf16 v[104:107], v[160:163], v[184:187], v[104:107]
	v_mfma_f32_16x16x32_bf16 v[96:99], v[168:171], v[184:187], v[96:99]
	v_mfma_f32_16x16x32_bf16 v[84:87], v[160:163], v[192:195], v[84:87]
	v_mfma_f32_16x16x32_bf16 v[80:83], v[168:171], v[192:195], v[80:83]
	v_mfma_f32_16x16x32_bf16 v[68:71], v[160:163], v[212:215], v[68:71]
	v_mfma_f32_16x16x32_bf16 v[64:67], v[168:171], v[212:215], v[64:67]
	s_setprio 0
	s_barrier
	s_add_i32 s58, s85, s66
	v_lshl_add_u64 v[216:217], s[56:57], 0, v[144:145]
	s_mov_b32 m0, s58
	ds_read_b128 v[172:175], v201 offset:16384
	ds_read_b128 v[176:179], v201 offset:17408
	ds_read_b128 v[180:183], v201 offset:18432
	ds_read_b128 v[184:187], v201 offset:19456
	ds_read_b128 v[188:191], v201 offset:20480
	ds_read_b128 v[192:195], v201 offset:21504
	ds_read_b128 v[204:207], v201 offset:22528
	ds_read_b128 v[212:215], v201 offset:23552
	global_load_lds_dwordx4 v[216:217], off
	s_add_i32 m0, s58, 0x2000
	s_add_u32 s90, s56, 0x40000
	v_lshl_add_u64 v[218:219], s[56:57], 0, v[146:147]
	s_addc_u32 s91, s57, 0
	s_add_i32 s58, s86, s66
	global_load_lds_dwordx4 v[218:219], off
	v_lshl_add_u64 v[220:221], s[90:91], 0, v[144:145]
	s_mov_b32 m0, s58
	v_lshl_add_u64 v[222:223], s[64:65], 0, v[146:147]
	global_load_lds_dwordx4 v[220:221], off
	v_lshl_add_u64 v[220:221], s[90:91], 0, v[146:147]
	s_add_i32 m0, s58, 0x2000
	s_nop 0
	global_load_lds_dwordx4 v[220:221], off
	s_waitcnt vmcnt(6)
	s_waitcnt lgkmcnt(0)
	s_barrier
	s_setprio 1
	s_waitcnt lgkmcnt(0)
	v_mfma_f32_16x16x32_bf16 v[60:63], v[100:103], v[172:175], v[60:63]
	v_mfma_f32_16x16x32_bf16 v[56:59], v[112:115], v[172:175], v[56:59]
	v_mfma_f32_16x16x32_bf16 v[44:47], v[100:103], v[180:183], v[44:47]
	v_mfma_f32_16x16x32_bf16 v[40:43], v[112:115], v[180:183], v[40:43]
	v_mfma_f32_16x16x32_bf16 v[28:31], v[100:103], v[188:191], v[28:31]
	v_mfma_f32_16x16x32_bf16 v[24:27], v[112:115], v[188:191], v[24:27]
	v_mfma_f32_16x16x32_bf16 v[12:15], v[100:103], v[204:207], v[12:15]
	v_mfma_f32_16x16x32_bf16 v[8:11], v[112:115], v[204:207], v[8:11]
	v_mfma_f32_16x16x32_bf16 v[60:63], v[108:111], v[176:179], v[60:63]
	v_mfma_f32_16x16x32_bf16 v[56:59], v[116:119], v[176:179], v[56:59]
	v_mfma_f32_16x16x32_bf16 v[44:47], v[108:111], v[184:187], v[44:47]
	v_mfma_f32_16x16x32_bf16 v[40:43], v[116:119], v[184:187], v[40:43]
	v_mfma_f32_16x16x32_bf16 v[28:31], v[108:111], v[192:195], v[28:31]
	v_mfma_f32_16x16x32_bf16 v[24:27], v[116:119], v[192:195], v[24:27]
	v_mfma_f32_16x16x32_bf16 v[12:15], v[108:111], v[212:215], v[12:15]
	v_mfma_f32_16x16x32_bf16 v[8:11], v[116:119], v[212:215], v[8:11]
	v_mfma_f32_16x16x32_bf16 v[52:55], v[156:159], v[172:175], v[52:55]
	v_mfma_f32_16x16x32_bf16 v[48:51], v[164:167], v[172:175], v[48:51]
	v_mfma_f32_16x16x32_bf16 v[36:39], v[156:159], v[180:183], v[36:39]
	v_mfma_f32_16x16x32_bf16 v[32:35], v[164:167], v[180:183], v[32:35]
	v_mfma_f32_16x16x32_bf16 v[20:23], v[156:159], v[188:191], v[20:23]
	v_mfma_f32_16x16x32_bf16 v[16:19], v[164:167], v[188:191], v[16:19]
	v_mfma_f32_16x16x32_bf16 v[4:7], v[156:159], v[204:207], v[4:7]
	v_mfma_f32_16x16x32_bf16 v[0:3], v[164:167], v[204:207], v[0:3]
	v_mfma_f32_16x16x32_bf16 v[52:55], v[160:163], v[176:179], v[52:55]
	v_mfma_f32_16x16x32_bf16 v[48:51], v[168:171], v[176:179], v[48:51]
	v_mfma_f32_16x16x32_bf16 v[36:39], v[160:163], v[184:187], v[36:39]
	v_mfma_f32_16x16x32_bf16 v[32:35], v[168:171], v[184:187], v[32:35]
	v_mfma_f32_16x16x32_bf16 v[20:23], v[160:163], v[192:195], v[20:23]
	v_mfma_f32_16x16x32_bf16 v[16:19], v[168:171], v[192:195], v[16:19]
	v_mfma_f32_16x16x32_bf16 v[4:7], v[160:163], v[212:215], v[4:7]
	v_mfma_f32_16x16x32_bf16 v[0:3], v[168:171], v[212:215], v[0:3]
	s_setprio 0
	s_barrier
	s_add_i32 s58, 0, 0x18000
	s_add_i32 s59, 0, 0x1c000
	v_add_u32_e32 v116, s58, v197
	v_add_u32_e32 v168, s59, v197
	ds_read_b128 v[100:103], v116
	ds_read_b128 v[108:111], v116 offset:1024
	ds_read_b128 v[112:115], v116 offset:2048
	ds_read_b128 v[116:119], v116 offset:3072
	ds_read_b128 v[156:159], v168
	ds_read_b128 v[160:163], v168 offset:1024
	ds_read_b128 v[164:167], v168 offset:2048
	ds_read_b128 v[168:171], v168 offset:3072
	v_lshl_add_u64 v[220:221], s[64:65], 0, v[144:145]
	s_mov_b32 m0, s67
	s_nop 0
	global_load_lds_dwordx4 v[220:221], off
	s_mov_b32 m0, s68
	s_nop 0
	global_load_lds_dwordx4 v[222:223], off
	s_add_u32 s64, s64, 0x40000
	s_addc_u32 s65, s65, 0
	s_mov_b32 m0, s69
	v_lshl_add_u64 v[224:225], s[64:65], 0, v[144:145]
	ds_read_b128 v[172:175], v201 offset:32768
	ds_read_b128 v[176:179], v201 offset:33792
	ds_read_b128 v[180:183], v201 offset:34816
	ds_read_b128 v[184:187], v201 offset:35840
	ds_read_b128 v[188:191], v201 offset:36864
	ds_read_b128 v[192:195], v201 offset:37888
	ds_read_b128 v[204:207], v201 offset:38912
	ds_read_b128 v[212:215], v201 offset:39936
	global_load_lds_dwordx4 v[224:225], off
	v_lshl_add_u64 v[224:225], s[64:65], 0, v[146:147]
	s_mov_b32 m0, s70
	s_nop 0
	global_load_lds_dwordx4 v[224:225], off
	s_waitcnt vmcnt(8)
	s_waitcnt lgkmcnt(0)
	s_barrier
	s_setprio 1
	s_waitcnt lgkmcnt(0)
	v_mfma_f32_16x16x32_bf16 v[140:143], v[100:103], v[172:175], v[140:143]
	v_mfma_f32_16x16x32_bf16 v[136:139], v[112:115], v[172:175], v[136:139]
	v_mfma_f32_16x16x32_bf16 v[124:127], v[100:103], v[180:183], v[124:127]
	v_mfma_f32_16x16x32_bf16 v[120:123], v[112:115], v[180:183], v[120:123]
	v_mfma_f32_16x16x32_bf16 v[92:95], v[100:103], v[188:191], v[92:95]
	v_mfma_f32_16x16x32_bf16 v[88:91], v[112:115], v[188:191], v[88:91]
	v_mfma_f32_16x16x32_bf16 v[76:79], v[100:103], v[204:207], v[76:79]
	v_mfma_f32_16x16x32_bf16 v[72:75], v[112:115], v[204:207], v[72:75]
	v_mfma_f32_16x16x32_bf16 v[140:143], v[108:111], v[176:179], v[140:143]
	v_mfma_f32_16x16x32_bf16 v[136:139], v[116:119], v[176:179], v[136:139]
	v_mfma_f32_16x16x32_bf16 v[124:127], v[108:111], v[184:187], v[124:127]
	v_mfma_f32_16x16x32_bf16 v[120:123], v[116:119], v[184:187], v[120:123]
	v_mfma_f32_16x16x32_bf16 v[92:95], v[108:111], v[192:195], v[92:95]
	v_mfma_f32_16x16x32_bf16 v[88:91], v[116:119], v[192:195], v[88:91]
	v_mfma_f32_16x16x32_bf16 v[76:79], v[108:111], v[212:215], v[76:79]
	v_mfma_f32_16x16x32_bf16 v[72:75], v[116:119], v[212:215], v[72:75]
	v_mfma_f32_16x16x32_bf16 v[132:135], v[156:159], v[172:175], v[132:135]
	v_mfma_f32_16x16x32_bf16 v[128:131], v[164:167], v[172:175], v[128:131]
	v_mfma_f32_16x16x32_bf16 v[104:107], v[156:159], v[180:183], v[104:107]
	v_mfma_f32_16x16x32_bf16 v[96:99], v[164:167], v[180:183], v[96:99]
	v_mfma_f32_16x16x32_bf16 v[84:87], v[156:159], v[188:191], v[84:87]
	v_mfma_f32_16x16x32_bf16 v[80:83], v[164:167], v[188:191], v[80:83]
	v_mfma_f32_16x16x32_bf16 v[68:71], v[156:159], v[204:207], v[68:71]
	v_mfma_f32_16x16x32_bf16 v[64:67], v[164:167], v[204:207], v[64:67]
	v_mfma_f32_16x16x32_bf16 v[132:135], v[160:163], v[176:179], v[132:135]
	v_mfma_f32_16x16x32_bf16 v[128:131], v[168:171], v[176:179], v[128:131]
	v_mfma_f32_16x16x32_bf16 v[104:107], v[160:163], v[184:187], v[104:107]
	v_mfma_f32_16x16x32_bf16 v[96:99], v[168:171], v[184:187], v[96:99]
	v_mfma_f32_16x16x32_bf16 v[84:87], v[160:163], v[192:195], v[84:87]
	v_mfma_f32_16x16x32_bf16 v[80:83], v[168:171], v[192:195], v[80:83]
	v_mfma_f32_16x16x32_bf16 v[68:71], v[160:163], v[212:215], v[68:71]
	v_mfma_f32_16x16x32_bf16 v[64:67], v[168:171], v[212:215], v[64:67]
	s_setprio 0
	s_barrier
	s_add_i32 s58, s58, s66
	v_lshl_add_u64 v[216:217], v[216:217], 0, s[36:37]
	s_mov_b32 m0, s58
	ds_read_b128 v[172:175], v201 offset:49152
	ds_read_b128 v[176:179], v201 offset:50176
	ds_read_b128 v[180:183], v201 offset:51200
	ds_read_b128 v[184:187], v201 offset:52224
	ds_read_b128 v[188:191], v201 offset:53248
	ds_read_b128 v[192:195], v201 offset:54272
	ds_read_b128 v[204:207], v201 offset:55296
	ds_read_b128 v[212:215], v201 offset:56320
	global_load_lds_dwordx4 v[216:217], off
	s_add_i32 m0, s58, 0x2000
	s_add_u32 s56, s56, 0x40080
	v_lshl_add_u64 v[216:217], v[218:219], 0, s[36:37]
	s_addc_u32 s57, s57, 0
	s_add_i32 s58, s59, s66
	global_load_lds_dwordx4 v[216:217], off
	v_lshl_add_u64 v[216:217], s[56:57], 0, v[144:145]
	s_mov_b32 m0, s58
	s_nop 0
	global_load_lds_dwordx4 v[216:217], off
	v_lshl_add_u64 v[216:217], s[56:57], 0, v[146:147]
	s_add_i32 m0, s58, 0x2000
	s_nop 0
	global_load_lds_dwordx4 v[216:217], off
	v_lshl_add_u64 v[216:217], v[220:221], 0, s[36:37]
	s_mov_b32 m0, s80
	s_nop 0
	global_load_lds_dwordx4 v[216:217], off
	v_lshl_add_u64 v[216:217], v[222:223], 0, s[36:37]
	s_mov_b32 m0, s81
	s_nop 0
	global_load_lds_dwordx4 v[216:217], off
	s_waitcnt vmcnt(6)
	s_waitcnt lgkmcnt(0)
	s_barrier
	s_setprio 1
	s_waitcnt lgkmcnt(0)
	v_mfma_f32_16x16x32_bf16 v[60:63], v[100:103], v[172:175], v[60:63]
	v_mfma_f32_16x16x32_bf16 v[56:59], v[112:115], v[172:175], v[56:59]
	v_mfma_f32_16x16x32_bf16 v[44:47], v[100:103], v[180:183], v[44:47]
	v_mfma_f32_16x16x32_bf16 v[40:43], v[112:115], v[180:183], v[40:43]
	v_mfma_f32_16x16x32_bf16 v[28:31], v[100:103], v[188:191], v[28:31]
	v_mfma_f32_16x16x32_bf16 v[24:27], v[112:115], v[188:191], v[24:27]
	v_mfma_f32_16x16x32_bf16 v[12:15], v[100:103], v[204:207], v[12:15]
	v_mfma_f32_16x16x32_bf16 v[8:11], v[112:115], v[204:207], v[8:11]
	v_mfma_f32_16x16x32_bf16 v[60:63], v[108:111], v[176:179], v[60:63]
	v_mfma_f32_16x16x32_bf16 v[56:59], v[116:119], v[176:179], v[56:59]
	v_mfma_f32_16x16x32_bf16 v[44:47], v[108:111], v[184:187], v[44:47]
	v_mfma_f32_16x16x32_bf16 v[40:43], v[116:119], v[184:187], v[40:43]
	v_mfma_f32_16x16x32_bf16 v[28:31], v[108:111], v[192:195], v[28:31]
	v_mfma_f32_16x16x32_bf16 v[24:27], v[116:119], v[192:195], v[24:27]
	v_mfma_f32_16x16x32_bf16 v[12:15], v[108:111], v[212:215], v[12:15]
	v_mfma_f32_16x16x32_bf16 v[8:11], v[116:119], v[212:215], v[8:11]
	v_mfma_f32_16x16x32_bf16 v[52:55], v[156:159], v[172:175], v[52:55]
	v_mfma_f32_16x16x32_bf16 v[48:51], v[164:167], v[172:175], v[48:51]
	v_mfma_f32_16x16x32_bf16 v[36:39], v[156:159], v[180:183], v[36:39]
	v_mfma_f32_16x16x32_bf16 v[32:35], v[164:167], v[180:183], v[32:35]
	v_mfma_f32_16x16x32_bf16 v[20:23], v[156:159], v[188:191], v[20:23]
	v_mfma_f32_16x16x32_bf16 v[16:19], v[164:167], v[188:191], v[16:19]
	v_mfma_f32_16x16x32_bf16 v[4:7], v[156:159], v[204:207], v[4:7]
	v_mfma_f32_16x16x32_bf16 v[0:3], v[164:167], v[204:207], v[0:3]
	v_mfma_f32_16x16x32_bf16 v[52:55], v[160:163], v[176:179], v[52:55]
	v_mfma_f32_16x16x32_bf16 v[48:51], v[168:171], v[176:179], v[48:51]
	v_mfma_f32_16x16x32_bf16 v[36:39], v[160:163], v[184:187], v[36:39]
	v_mfma_f32_16x16x32_bf16 v[32:35], v[168:171], v[184:187], v[32:35]
	v_mfma_f32_16x16x32_bf16 v[20:23], v[160:163], v[192:195], v[20:23]
	v_mfma_f32_16x16x32_bf16 v[16:19], v[168:171], v[192:195], v[16:19]
	v_mfma_f32_16x16x32_bf16 v[4:7], v[160:163], v[212:215], v[4:7]
	v_mfma_f32_16x16x32_bf16 v[0:3], v[168:171], v[212:215], v[0:3]
	s_setprio 0
	s_barrier
	s_add_i32 s88, s88, 2
	s_add_u32 s54, s54, 0x100
	s_addc_u32 s55, s55, 0
	s_add_u32 s87, s87, 0x100
	s_addc_u32 s33, s33, 0
	s_cmp_gt_u32 s88, 13
	s_cbranch_scc0 .LBB0_544
	s_and_b64 vcc, exec, s[38:39]
	s_cbranch_vccz .LBB0_547
	s_barrier

.LBB0_639:
	ds_read_b128 v[144:147], v151
	ds_read_b128 v[154:157], v151 offset:1024
	ds_read_b128 v[158:161], v151 offset:2048
	ds_read_b128 v[162:165], v151 offset:3072
	ds_read_b128 v[166:169], v152
	ds_read_b128 v[170:173], v152 offset:1024
	ds_read_b128 v[174:177], v152 offset:2048
	ds_read_b128 v[178:181], v152 offset:3072
	s_add_u32 s40, s38, 0xfffc0080
	s_addc_u32 s41, s39, -1
	s_cmp_eq_u32 s68, 12
	s_cselect_b32 s43, s21, s41
	s_cselect_b32 s42, s65, s40
	s_cselect_b32 s41, s17, s33
	s_cselect_b32 s40, s66, s67
	v_lshl_add_u64 v[206:207], s[38:39], 0, v[136:137]
	s_add_i32 m0, s37, 0xc000
	ds_read_b128 v[182:185], v153
	ds_read_b128 v[186:189], v153 offset:1024
	ds_read_b128 v[190:193], v153 offset:2048
	ds_read_b128 v[194:197], v153 offset:3072
	ds_read_b128 v[198:201], v153 offset:4096
	ds_read_b128 v[202:205], v153 offset:5120
	ds_read_b128 v[212:215], v153 offset:6144
	ds_read_b128 v[216:219], v153 offset:7168
	global_load_lds_dwordx4 v[206:207], off
	v_lshl_add_u64 v[206:207], s[38:39], 0, v[138:139]
	s_add_i32 m0, s37, 0xe000
	s_nop 0
	global_load_lds_dwordx4 v[206:207], off
	s_waitcnt vmcnt(8)
	s_waitcnt lgkmcnt(0)
	s_barrier
	s_setprio 1
	s_waitcnt lgkmcnt(0)
	v_mfma_f32_16x16x32_bf16 v[124:127], v[144:147], v[182:185], v[124:127]
	v_mfma_f32_16x16x32_bf16 v[116:119], v[158:161], v[182:185], v[116:119]
	v_mfma_f32_16x16x32_bf16 v[108:111], v[144:147], v[190:193], v[108:111]
	v_mfma_f32_16x16x32_bf16 v[100:103], v[158:161], v[190:193], v[100:103]
	v_mfma_f32_16x16x32_bf16 v[92:95], v[144:147], v[198:201], v[92:95]
	v_mfma_f32_16x16x32_bf16 v[84:87], v[158:161], v[198:201], v[84:87]
	v_mfma_f32_16x16x32_bf16 v[76:79], v[144:147], v[212:215], v[76:79]
	v_mfma_f32_16x16x32_bf16 v[68:71], v[158:161], v[212:215], v[68:71]
	v_mfma_f32_16x16x32_bf16 v[124:127], v[154:157], v[186:189], v[124:127]
	v_mfma_f32_16x16x32_bf16 v[116:119], v[162:165], v[186:189], v[116:119]
	v_mfma_f32_16x16x32_bf16 v[108:111], v[154:157], v[194:197], v[108:111]
	v_mfma_f32_16x16x32_bf16 v[100:103], v[162:165], v[194:197], v[100:103]
	v_mfma_f32_16x16x32_bf16 v[92:95], v[154:157], v[202:205], v[92:95]
	v_mfma_f32_16x16x32_bf16 v[84:87], v[162:165], v[202:205], v[84:87]
	v_mfma_f32_16x16x32_bf16 v[76:79], v[154:157], v[216:219], v[76:79]
	v_mfma_f32_16x16x32_bf16 v[68:71], v[162:165], v[216:219], v[68:71]
	v_mfma_f32_16x16x32_bf16 v[120:123], v[166:169], v[182:185], v[120:123]
	v_mfma_f32_16x16x32_bf16 v[112:115], v[174:177], v[182:185], v[112:115]
	v_mfma_f32_16x16x32_bf16 v[104:107], v[166:169], v[190:193], v[104:107]
	v_mfma_f32_16x16x32_bf16 v[96:99], v[174:177], v[190:193], v[96:99]
	v_mfma_f32_16x16x32_bf16 v[88:91], v[166:169], v[198:201], v[88:91]
	v_mfma_f32_16x16x32_bf16 v[80:83], v[174:177], v[198:201], v[80:83]
	v_mfma_f32_16x16x32_bf16 v[72:75], v[166:169], v[212:215], v[72:75]
	v_mfma_f32_16x16x32_bf16 v[64:67], v[174:177], v[212:215], v[64:67]
	v_mfma_f32_16x16x32_bf16 v[120:123], v[170:173], v[186:189], v[120:123]
	v_mfma_f32_16x16x32_bf16 v[112:115], v[178:181], v[186:189], v[112:115]
	v_mfma_f32_16x16x32_bf16 v[104:107], v[170:173], v[194:197], v[104:107]
	v_mfma_f32_16x16x32_bf16 v[96:99], v[178:181], v[194:197], v[96:99]
	v_mfma_f32_16x16x32_bf16 v[88:91], v[170:173], v[202:205], v[88:91]
	v_mfma_f32_16x16x32_bf16 v[80:83], v[178:181], v[202:205], v[80:83]
	v_mfma_f32_16x16x32_bf16 v[72:75], v[170:173], v[216:219], v[72:75]
	v_mfma_f32_16x16x32_bf16 v[64:67], v[178:181], v[216:219], v[64:67]
	s_setprio 0
	s_barrier
	s_add_i32 s58, s55, s44
	v_lshl_add_u64 v[206:207], s[40:41], 0, v[132:133]
	s_mov_b32 m0, s58
	ds_read_b128 v[182:185], v153 offset:16384
	ds_read_b128 v[186:189], v153 offset:17408
	ds_read_b128 v[190:193], v153 offset:18432
	ds_read_b128 v[194:197], v153 offset:19456
	ds_read_b128 v[198:201], v153 offset:20480
	ds_read_b128 v[202:205], v153 offset:21504
	ds_read_b128 v[212:215], v153 offset:22528
	ds_read_b128 v[216:219], v153 offset:23552
	global_load_lds_dwordx4 v[206:207], off
	s_add_i32 m0, s58, 0x2000
	s_add_u32 s70, s40, 0x40000
	v_lshl_add_u64 v[220:221], s[40:41], 0, v[128:129]
	s_addc_u32 s71, s41, 0
	s_add_i32 s58, s56, s44
	global_load_lds_dwordx4 v[220:221], off
	v_lshl_add_u64 v[222:223], s[70:71], 0, v[132:133]
	s_mov_b32 m0, s58
	v_lshl_add_u64 v[224:225], s[42:43], 0, v[130:131]
	global_load_lds_dwordx4 v[222:223], off
	v_lshl_add_u64 v[222:223], s[70:71], 0, v[128:129]
	s_add_i32 m0, s58, 0x2000
	s_nop 0
	global_load_lds_dwordx4 v[222:223], off
	s_waitcnt vmcnt(6)
	s_waitcnt lgkmcnt(0)
	s_barrier
	s_setprio 1
	s_waitcnt lgkmcnt(0)
	v_mfma_f32_16x16x32_bf16 v[60:63], v[144:147], v[182:185], v[60:63]
	v_mfma_f32_16x16x32_bf16 v[52:55], v[158:161], v[182:185], v[52:55]
	v_mfma_f32_16x16x32_bf16 v[44:47], v[144:147], v[190:193], v[44:47]
	v_mfma_f32_16x16x32_bf16 v[36:39], v[158:161], v[190:193], v[36:39]
	v_mfma_f32_16x16x32_bf16 v[28:31], v[144:147], v[198:201], v[28:31]
	v_mfma_f32_16x16x32_bf16 v[20:23], v[158:161], v[198:201], v[20:23]
	v_mfma_f32_16x16x32_bf16 v[12:15], v[144:147], v[212:215], v[12:15]
	v_mfma_f32_16x16x32_bf16 v[4:7], v[158:161], v[212:215], v[4:7]
	v_mfma_f32_16x16x32_bf16 v[60:63], v[154:157], v[186:189], v[60:63]
	v_mfma_f32_16x16x32_bf16 v[52:55], v[162:165], v[186:189], v[52:55]
	v_mfma_f32_16x16x32_bf16 v[44:47], v[154:157], v[194:197], v[44:47]
	v_mfma_f32_16x16x32_bf16 v[36:39], v[162:165], v[194:197], v[36:39]
	v_mfma_f32_16x16x32_bf16 v[28:31], v[154:157], v[202:205], v[28:31]
	v_mfma_f32_16x16x32_bf16 v[20:23], v[162:165], v[202:205], v[20:23]
	v_mfma_f32_16x16x32_bf16 v[12:15], v[154:157], v[216:219], v[12:15]
	v_mfma_f32_16x16x32_bf16 v[4:7], v[162:165], v[216:219], v[4:7]
	v_mfma_f32_16x16x32_bf16 v[56:59], v[166:169], v[182:185], v[56:59]
	v_mfma_f32_16x16x32_bf16 v[48:51], v[174:177], v[182:185], v[48:51]
	v_mfma_f32_16x16x32_bf16 v[40:43], v[166:169], v[190:193], v[40:43]
	v_mfma_f32_16x16x32_bf16 v[32:35], v[174:177], v[190:193], v[32:35]
	v_mfma_f32_16x16x32_bf16 v[24:27], v[166:169], v[198:201], v[24:27]
	v_mfma_f32_16x16x32_bf16 v[16:19], v[174:177], v[198:201], v[16:19]
	v_mfma_f32_16x16x32_bf16 v[8:11], v[166:169], v[212:215], v[8:11]
	v_mfma_f32_16x16x32_bf16 v[0:3], v[174:177], v[212:215], v[0:3]
	v_mfma_f32_16x16x32_bf16 v[56:59], v[170:173], v[186:189], v[56:59]
	v_mfma_f32_16x16x32_bf16 v[48:51], v[178:181], v[186:189], v[48:51]
	v_mfma_f32_16x16x32_bf16 v[40:43], v[170:173], v[194:197], v[40:43]
	v_mfma_f32_16x16x32_bf16 v[32:35], v[178:181], v[194:197], v[32:35]
	v_mfma_f32_16x16x32_bf16 v[24:27], v[170:173], v[202:205], v[24:27]
	v_mfma_f32_16x16x32_bf16 v[16:19], v[178:181], v[202:205], v[16:19]
	v_mfma_f32_16x16x32_bf16 v[8:11], v[170:173], v[216:219], v[8:11]
	v_mfma_f32_16x16x32_bf16 v[0:3], v[178:181], v[216:219], v[0:3]
	s_setprio 0
	s_barrier
	s_add_i32 s58, 0, 0x18000
	s_add_i32 s59, 0, 0x1c000
	v_add_u32_e32 v162, s58, v149
	v_add_u32_e32 v178, s59, v149
	ds_read_b128 v[144:147], v162
	ds_read_b128 v[154:157], v162 offset:1024
	ds_read_b128 v[158:161], v162 offset:2048
	ds_read_b128 v[162:165], v162 offset:3072
	ds_read_b128 v[166:169], v178
	ds_read_b128 v[170:173], v178 offset:1024
	ds_read_b128 v[174:177], v178 offset:2048
	ds_read_b128 v[178:181], v178 offset:3072
	v_lshl_add_u64 v[222:223], s[42:43], 0, v[134:135]
	s_mov_b32 m0, s37
	s_nop 0
	global_load_lds_dwordx4 v[222:223], off
	s_mov_b32 m0, s47
	s_nop 0
	global_load_lds_dwordx4 v[224:225], off
	s_add_u32 s42, s42, 0x40000
	s_addc_u32 s43, s43, 0
	s_mov_b32 m0, s48
	v_lshl_add_u64 v[226:227], s[42:43], 0, v[134:135]
	ds_read_b128 v[182:185], v153 offset:32768
	ds_read_b128 v[186:189], v153 offset:33792
	ds_read_b128 v[190:193], v153 offset:34816
	ds_read_b128 v[194:197], v153 offset:35840
	ds_read_b128 v[198:201], v153 offset:36864
	ds_read_b128 v[202:205], v153 offset:37888
	ds_read_b128 v[212:215], v153 offset:38912
	ds_read_b128 v[216:219], v153 offset:39936
	global_load_lds_dwordx4 v[226:227], off
	v_lshl_add_u64 v[226:227], s[42:43], 0, v[130:131]
	s_mov_b32 m0, s49
	s_nop 0
	global_load_lds_dwordx4 v[226:227], off
	s_waitcnt vmcnt(8)
	s_waitcnt lgkmcnt(0)
	s_barrier
	s_setprio 1
	s_waitcnt lgkmcnt(0)
	v_mfma_f32_16x16x32_bf16 v[124:127], v[144:147], v[182:185], v[124:127]
	v_mfma_f32_16x16x32_bf16 v[116:119], v[158:161], v[182:185], v[116:119]
	v_mfma_f32_16x16x32_bf16 v[108:111], v[144:147], v[190:193], v[108:111]
	v_mfma_f32_16x16x32_bf16 v[100:103], v[158:161], v[190:193], v[100:103]
	v_mfma_f32_16x16x32_bf16 v[92:95], v[144:147], v[198:201], v[92:95]
	v_mfma_f32_16x16x32_bf16 v[84:87], v[158:161], v[198:201], v[84:87]
	v_mfma_f32_16x16x32_bf16 v[76:79], v[144:147], v[212:215], v[76:79]
	v_mfma_f32_16x16x32_bf16 v[68:71], v[158:161], v[212:215], v[68:71]
	v_mfma_f32_16x16x32_bf16 v[124:127], v[154:157], v[186:189], v[124:127]
	v_mfma_f32_16x16x32_bf16 v[116:119], v[162:165], v[186:189], v[116:119]
	v_mfma_f32_16x16x32_bf16 v[108:111], v[154:157], v[194:197], v[108:111]
	v_mfma_f32_16x16x32_bf16 v[100:103], v[162:165], v[194:197], v[100:103]
	v_mfma_f32_16x16x32_bf16 v[92:95], v[154:157], v[202:205], v[92:95]
	v_mfma_f32_16x16x32_bf16 v[84:87], v[162:165], v[202:205], v[84:87]
	v_mfma_f32_16x16x32_bf16 v[76:79], v[154:157], v[216:219], v[76:79]
	v_mfma_f32_16x16x32_bf16 v[68:71], v[162:165], v[216:219], v[68:71]
	v_mfma_f32_16x16x32_bf16 v[120:123], v[166:169], v[182:185], v[120:123]
	v_mfma_f32_16x16x32_bf16 v[112:115], v[174:177], v[182:185], v[112:115]
	v_mfma_f32_16x16x32_bf16 v[104:107], v[166:169], v[190:193], v[104:107]
	v_mfma_f32_16x16x32_bf16 v[96:99], v[174:177], v[190:193], v[96:99]
	v_mfma_f32_16x16x32_bf16 v[88:91], v[166:169], v[198:201], v[88:91]
	v_mfma_f32_16x16x32_bf16 v[80:83], v[174:177], v[198:201], v[80:83]
	v_mfma_f32_16x16x32_bf16 v[72:75], v[166:169], v[212:215], v[72:75]
	v_mfma_f32_16x16x32_bf16 v[64:67], v[174:177], v[212:215], v[64:67]
	v_mfma_f32_16x16x32_bf16 v[120:123], v[170:173], v[186:189], v[120:123]
	v_mfma_f32_16x16x32_bf16 v[112:115], v[178:181], v[186:189], v[112:115]
	v_mfma_f32_16x16x32_bf16 v[104:107], v[170:173], v[194:197], v[104:107]
	v_mfma_f32_16x16x32_bf16 v[96:99], v[178:181], v[194:197], v[96:99]
	v_mfma_f32_16x16x32_bf16 v[88:91], v[170:173], v[202:205], v[88:91]
	v_mfma_f32_16x16x32_bf16 v[80:83], v[178:181], v[202:205], v[80:83]
	v_mfma_f32_16x16x32_bf16 v[72:75], v[170:173], v[216:219], v[72:75]
	v_mfma_f32_16x16x32_bf16 v[64:67], v[178:181], v[216:219], v[64:67]
	s_setprio 0
	s_barrier
	s_add_i32 s42, s58, s44
	v_lshl_add_u64 v[206:207], v[206:207], 0, s[6:7]
	s_mov_b32 m0, s42
	ds_read_b128 v[182:185], v153 offset:49152
	ds_read_b128 v[186:189], v153 offset:50176
	ds_read_b128 v[190:193], v153 offset:51200
	ds_read_b128 v[194:197], v153 offset:52224
	ds_read_b128 v[198:201], v153 offset:53248
	ds_read_b128 v[202:205], v153 offset:54272
	ds_read_b128 v[212:215], v153 offset:55296
	ds_read_b128 v[216:219], v153 offset:56320
	global_load_lds_dwordx4 v[206:207], off
	s_add_i32 m0, s42, 0x2000
	s_add_u32 s40, s40, 0x40080
	v_lshl_add_u64 v[206:207], v[220:221], 0, s[6:7]
	s_addc_u32 s41, s41, 0
	s_add_i32 s42, s59, s44
	global_load_lds_dwordx4 v[206:207], off
	v_lshl_add_u64 v[206:207], s[40:41], 0, v[132:133]
	s_mov_b32 m0, s42
	s_nop 0
	global_load_lds_dwordx4 v[206:207], off
	v_lshl_add_u64 v[206:207], s[40:41], 0, v[128:129]
	s_add_i32 m0, s42, 0x2000
	s_nop 0
	global_load_lds_dwordx4 v[206:207], off
	v_lshl_add_u64 v[206:207], v[222:223], 0, s[6:7]
	s_mov_b32 m0, s51
	s_nop 0
	global_load_lds_dwordx4 v[206:207], off
	v_lshl_add_u64 v[206:207], v[224:225], 0, s[6:7]
	s_mov_b32 m0, s52
	s_nop 0
	global_load_lds_dwordx4 v[206:207], off
	s_waitcnt vmcnt(6)
	s_waitcnt lgkmcnt(0)
	s_barrier
	s_setprio 1
	s_waitcnt lgkmcnt(0)
	v_mfma_f32_16x16x32_bf16 v[60:63], v[144:147], v[182:185], v[60:63]
	v_mfma_f32_16x16x32_bf16 v[52:55], v[158:161], v[182:185], v[52:55]
	v_mfma_f32_16x16x32_bf16 v[44:47], v[144:147], v[190:193], v[44:47]
	v_mfma_f32_16x16x32_bf16 v[36:39], v[158:161], v[190:193], v[36:39]
	v_mfma_f32_16x16x32_bf16 v[28:31], v[144:147], v[198:201], v[28:31]
	v_mfma_f32_16x16x32_bf16 v[20:23], v[158:161], v[198:201], v[20:23]
	v_mfma_f32_16x16x32_bf16 v[12:15], v[144:147], v[212:215], v[12:15]
	v_mfma_f32_16x16x32_bf16 v[4:7], v[158:161], v[212:215], v[4:7]
	v_mfma_f32_16x16x32_bf16 v[60:63], v[154:157], v[186:189], v[60:63]
	v_mfma_f32_16x16x32_bf16 v[52:55], v[162:165], v[186:189], v[52:55]
	v_mfma_f32_16x16x32_bf16 v[44:47], v[154:157], v[194:197], v[44:47]
	v_mfma_f32_16x16x32_bf16 v[36:39], v[162:165], v[194:197], v[36:39]
	v_mfma_f32_16x16x32_bf16 v[28:31], v[154:157], v[202:205], v[28:31]
	v_mfma_f32_16x16x32_bf16 v[20:23], v[162:165], v[202:205], v[20:23]
	v_mfma_f32_16x16x32_bf16 v[12:15], v[154:157], v[216:219], v[12:15]
	v_mfma_f32_16x16x32_bf16 v[4:7], v[162:165], v[216:219], v[4:7]
	v_mfma_f32_16x16x32_bf16 v[56:59], v[166:169], v[182:185], v[56:59]
	v_mfma_f32_16x16x32_bf16 v[48:51], v[174:177], v[182:185], v[48:51]
	v_mfma_f32_16x16x32_bf16 v[40:43], v[166:169], v[190:193], v[40:43]
	v_mfma_f32_16x16x32_bf16 v[32:35], v[174:177], v[190:193], v[32:35]
	v_mfma_f32_16x16x32_bf16 v[24:27], v[166:169], v[198:201], v[24:27]
	v_mfma_f32_16x16x32_bf16 v[16:19], v[174:177], v[198:201], v[16:19]
	v_mfma_f32_16x16x32_bf16 v[8:11], v[166:169], v[212:215], v[8:11]
	v_mfma_f32_16x16x32_bf16 v[0:3], v[174:177], v[212:215], v[0:3]
	v_mfma_f32_16x16x32_bf16 v[56:59], v[170:173], v[186:189], v[56:59]
	v_mfma_f32_16x16x32_bf16 v[48:51], v[178:181], v[186:189], v[48:51]
	v_mfma_f32_16x16x32_bf16 v[40:43], v[170:173], v[194:197], v[40:43]
	v_mfma_f32_16x16x32_bf16 v[32:35], v[178:181], v[194:197], v[32:35]
	v_mfma_f32_16x16x32_bf16 v[24:27], v[170:173], v[202:205], v[24:27]
	v_mfma_f32_16x16x32_bf16 v[16:19], v[178:181], v[202:205], v[16:19]
	v_mfma_f32_16x16x32_bf16 v[8:11], v[170:173], v[216:219], v[8:11]
	v_mfma_f32_16x16x32_bf16 v[0:3], v[178:181], v[216:219], v[0:3]
	s_setprio 0
	s_barrier
	s_add_i32 s68, s68, 2
	s_add_u32 s38, s38, 0x100
	s_addc_u32 s39, s39, 0
	s_add_u32 s67, s67, 0x100
	s_addc_u32 s33, s33, 0
	s_cmp_gt_u32 s68, 13
	s_cbranch_scc0 .LBB0_639
	s_and_b64 vcc, exec, s[8:9]
	s_cbranch_vccz .LBB0_642
	s_barrier

.LBB0_722:
	ds_read_b128 v[96:99], v185
	ds_read_b128 v[100:103], v185 offset:1024
	ds_read_b128 v[104:107], v185 offset:2048
	ds_read_b128 v[108:111], v185 offset:3072
	ds_read_b128 v[156:159], v186
	ds_read_b128 v[160:163], v186 offset:1024
	ds_read_b128 v[164:167], v186 offset:2048
	ds_read_b128 v[168:171], v186 offset:3072
	s_add_u32 s28, s26, 0x100
	s_addc_u32 s29, s27, 0
	s_cmp_eq_u32 s57, 40
	s_cselect_b32 s37, s7, s29
	s_cselect_b32 s36, s6, s28
	s_cselect_b32 s35, s23, s56
	s_cselect_b32 s34, s22, s55
	v_lshl_add_u64 v[180:181], s[26:27], 0, v[148:149]
	s_add_i32 m0, s15, 0xc000
	ds_read_b128 v[172:175], v187
	ds_read_b128 v[176:179], v187 offset:1024
	ds_read_b128 v[190:193], v187 offset:2048
	ds_read_b128 v[194:197], v187 offset:3072
	ds_read_b128 v[198:201], v187 offset:4096
	ds_read_b128 v[202:205], v187 offset:5120
	ds_read_b128 v[206:209], v187 offset:6144
	ds_read_b128 v[212:215], v187 offset:7168
	global_load_lds_dwordx4 v[180:181], off
	v_lshl_add_u64 v[180:181], s[26:27], 0, v[150:151]
	s_add_i32 m0, s15, 0xe000
	s_nop 0
	global_load_lds_dwordx4 v[180:181], off
	s_waitcnt vmcnt(8)
	s_waitcnt lgkmcnt(0)
	s_barrier
	s_setprio 1
	s_waitcnt lgkmcnt(0)
	v_mfma_f32_16x16x32_bf16 v[140:143], v[96:99], v[172:175], v[140:143]
	v_mfma_f32_16x16x32_bf16 v[136:139], v[104:107], v[172:175], v[136:139]
	v_mfma_f32_16x16x32_bf16 v[124:127], v[96:99], v[190:193], v[124:127]
	v_mfma_f32_16x16x32_bf16 v[120:123], v[104:107], v[190:193], v[120:123]
	v_mfma_f32_16x16x32_bf16 v[92:95], v[96:99], v[198:201], v[92:95]
	v_mfma_f32_16x16x32_bf16 v[88:91], v[104:107], v[198:201], v[88:91]
	v_mfma_f32_16x16x32_bf16 v[76:79], v[96:99], v[206:209], v[76:79]
	v_mfma_f32_16x16x32_bf16 v[72:75], v[104:107], v[206:209], v[72:75]
	v_mfma_f32_16x16x32_bf16 v[140:143], v[100:103], v[176:179], v[140:143]
	v_mfma_f32_16x16x32_bf16 v[136:139], v[108:111], v[176:179], v[136:139]
	v_mfma_f32_16x16x32_bf16 v[124:127], v[100:103], v[194:197], v[124:127]
	v_mfma_f32_16x16x32_bf16 v[120:123], v[108:111], v[194:197], v[120:123]
	v_mfma_f32_16x16x32_bf16 v[92:95], v[100:103], v[202:205], v[92:95]
	v_mfma_f32_16x16x32_bf16 v[88:91], v[108:111], v[202:205], v[88:91]
	v_mfma_f32_16x16x32_bf16 v[76:79], v[100:103], v[212:215], v[76:79]
	v_mfma_f32_16x16x32_bf16 v[72:75], v[108:111], v[212:215], v[72:75]
	v_mfma_f32_16x16x32_bf16 v[132:135], v[156:159], v[172:175], v[132:135]
	v_mfma_f32_16x16x32_bf16 v[128:131], v[164:167], v[172:175], v[128:131]
	v_mfma_f32_16x16x32_bf16 v[116:119], v[156:159], v[190:193], v[116:119]
	v_mfma_f32_16x16x32_bf16 v[112:115], v[164:167], v[190:193], v[112:115]
	v_mfma_f32_16x16x32_bf16 v[84:87], v[156:159], v[198:201], v[84:87]
	v_mfma_f32_16x16x32_bf16 v[80:83], v[164:167], v[198:201], v[80:83]
	v_mfma_f32_16x16x32_bf16 v[68:71], v[156:159], v[206:209], v[68:71]
	v_mfma_f32_16x16x32_bf16 v[64:67], v[164:167], v[206:209], v[64:67]
	v_mfma_f32_16x16x32_bf16 v[132:135], v[160:163], v[176:179], v[132:135]
	v_mfma_f32_16x16x32_bf16 v[128:131], v[168:171], v[176:179], v[128:131]
	v_mfma_f32_16x16x32_bf16 v[116:119], v[160:163], v[194:197], v[116:119]
	v_mfma_f32_16x16x32_bf16 v[112:115], v[168:171], v[194:197], v[112:115]
	v_mfma_f32_16x16x32_bf16 v[84:87], v[160:163], v[202:205], v[84:87]
	v_mfma_f32_16x16x32_bf16 v[80:83], v[168:171], v[202:205], v[80:83]
	v_mfma_f32_16x16x32_bf16 v[68:71], v[160:163], v[212:215], v[68:71]
	v_mfma_f32_16x16x32_bf16 v[64:67], v[168:171], v[212:215], v[64:67]
	s_setprio 0
	s_barrier
	s_add_i32 s26, s49, s3
	v_lshl_add_u64 v[180:181], s[34:35], 0, v[144:145]
	s_mov_b32 m0, s26
	ds_read_b128 v[172:175], v187 offset:16384
	ds_read_b128 v[176:179], v187 offset:17408
	ds_read_b128 v[190:193], v187 offset:18432
	ds_read_b128 v[194:197], v187 offset:19456
	ds_read_b128 v[198:201], v187 offset:20480
	ds_read_b128 v[202:205], v187 offset:21504
	ds_read_b128 v[206:209], v187 offset:22528
	ds_read_b128 v[212:215], v187 offset:23552
	global_load_lds_dwordx4 v[180:181], off
	s_add_i32 m0, s26, 0x2000
	s_add_u32 s26, s34, 0xb0000
	v_lshl_add_u64 v[216:217], s[34:35], 0, v[146:147]
	s_addc_u32 s27, s35, 0
	s_add_i32 s58, s50, s3
	global_load_lds_dwordx4 v[216:217], off
	v_lshl_add_u64 v[218:219], s[26:27], 0, v[144:145]
	s_mov_b32 m0, s58
	v_lshl_add_u64 v[220:221], s[36:37], 0, v[146:147]
	global_load_lds_dwordx4 v[218:219], off
	v_lshl_add_u64 v[218:219], s[26:27], 0, v[146:147]
	s_add_i32 m0, s58, 0x2000
	s_nop 0
	global_load_lds_dwordx4 v[218:219], off
	s_waitcnt vmcnt(6)
	s_waitcnt lgkmcnt(0)
	s_barrier
	s_setprio 1
	s_waitcnt lgkmcnt(0)
	v_mfma_f32_16x16x32_bf16 v[60:63], v[96:99], v[172:175], v[60:63]
	v_mfma_f32_16x16x32_bf16 v[56:59], v[104:107], v[172:175], v[56:59]
	v_mfma_f32_16x16x32_bf16 v[44:47], v[96:99], v[190:193], v[44:47]
	v_mfma_f32_16x16x32_bf16 v[40:43], v[104:107], v[190:193], v[40:43]
	v_mfma_f32_16x16x32_bf16 v[28:31], v[96:99], v[198:201], v[28:31]
	v_mfma_f32_16x16x32_bf16 v[24:27], v[104:107], v[198:201], v[24:27]
	v_mfma_f32_16x16x32_bf16 v[12:15], v[96:99], v[206:209], v[12:15]
	v_mfma_f32_16x16x32_bf16 v[8:11], v[104:107], v[206:209], v[8:11]
	v_mfma_f32_16x16x32_bf16 v[60:63], v[100:103], v[176:179], v[60:63]
	v_mfma_f32_16x16x32_bf16 v[56:59], v[108:111], v[176:179], v[56:59]
	v_mfma_f32_16x16x32_bf16 v[44:47], v[100:103], v[194:197], v[44:47]
	v_mfma_f32_16x16x32_bf16 v[40:43], v[108:111], v[194:197], v[40:43]
	v_mfma_f32_16x16x32_bf16 v[28:31], v[100:103], v[202:205], v[28:31]
	v_mfma_f32_16x16x32_bf16 v[24:27], v[108:111], v[202:205], v[24:27]
	v_mfma_f32_16x16x32_bf16 v[12:15], v[100:103], v[212:215], v[12:15]
	v_mfma_f32_16x16x32_bf16 v[8:11], v[108:111], v[212:215], v[8:11]
	v_mfma_f32_16x16x32_bf16 v[52:55], v[156:159], v[172:175], v[52:55]
	v_mfma_f32_16x16x32_bf16 v[48:51], v[164:167], v[172:175], v[48:51]
	v_mfma_f32_16x16x32_bf16 v[36:39], v[156:159], v[190:193], v[36:39]
	v_mfma_f32_16x16x32_bf16 v[32:35], v[164:167], v[190:193], v[32:35]
	v_mfma_f32_16x16x32_bf16 v[20:23], v[156:159], v[198:201], v[20:23]
	v_mfma_f32_16x16x32_bf16 v[16:19], v[164:167], v[198:201], v[16:19]
	v_mfma_f32_16x16x32_bf16 v[4:7], v[156:159], v[206:209], v[4:7]
	v_mfma_f32_16x16x32_bf16 v[0:3], v[164:167], v[206:209], v[0:3]
	v_mfma_f32_16x16x32_bf16 v[52:55], v[160:163], v[176:179], v[52:55]
	v_mfma_f32_16x16x32_bf16 v[48:51], v[168:171], v[176:179], v[48:51]
	v_mfma_f32_16x16x32_bf16 v[36:39], v[160:163], v[194:197], v[36:39]
	v_mfma_f32_16x16x32_bf16 v[32:35], v[168:171], v[194:197], v[32:35]
	v_mfma_f32_16x16x32_bf16 v[20:23], v[160:163], v[202:205], v[20:23]
	v_mfma_f32_16x16x32_bf16 v[16:19], v[168:171], v[202:205], v[16:19]
	v_mfma_f32_16x16x32_bf16 v[4:7], v[160:163], v[212:215], v[4:7]
	v_mfma_f32_16x16x32_bf16 v[0:3], v[168:171], v[212:215], v[0:3]
	s_setprio 0
	s_barrier
	s_add_i32 s58, 0, 0x18000
	s_add_i32 s59, 0, 0x1c000
	v_add_u32_e32 v108, s58, v183
	v_add_u32_e32 v168, s59, v183
	ds_read_b128 v[96:99], v108
	ds_read_b128 v[100:103], v108 offset:1024
	ds_read_b128 v[104:107], v108 offset:2048
	ds_read_b128 v[108:111], v108 offset:3072
	ds_read_b128 v[156:159], v168
	ds_read_b128 v[160:163], v168 offset:1024
	ds_read_b128 v[164:167], v168 offset:2048
	ds_read_b128 v[168:171], v168 offset:3072
	v_lshl_add_u64 v[218:219], s[36:37], 0, v[144:145]
	s_mov_b32 m0, s15
	s_nop 0
	global_load_lds_dwordx4 v[218:219], off
	s_mov_b32 m0, s33
	s_nop 0
	global_load_lds_dwordx4 v[220:221], off
	s_add_u32 s26, s36, 0xb0000
	s_addc_u32 s27, s37, 0
	s_mov_b32 m0, s38
	v_lshl_add_u64 v[222:223], s[26:27], 0, v[144:145]
	ds_read_b128 v[172:175], v187 offset:32768
	ds_read_b128 v[176:179], v187 offset:33792
	ds_read_b128 v[190:193], v187 offset:34816
	ds_read_b128 v[194:197], v187 offset:35840
	ds_read_b128 v[198:201], v187 offset:36864
	ds_read_b128 v[202:205], v187 offset:37888
	ds_read_b128 v[206:209], v187 offset:38912
	ds_read_b128 v[212:215], v187 offset:39936
	global_load_lds_dwordx4 v[222:223], off
	v_lshl_add_u64 v[222:223], s[26:27], 0, v[146:147]
	s_mov_b32 m0, s39
	s_nop 0
	global_load_lds_dwordx4 v[222:223], off
	s_waitcnt vmcnt(8)
	s_waitcnt lgkmcnt(0)
	s_barrier
	s_setprio 1
	s_waitcnt lgkmcnt(0)
	v_mfma_f32_16x16x32_bf16 v[140:143], v[96:99], v[172:175], v[140:143]
	v_mfma_f32_16x16x32_bf16 v[136:139], v[104:107], v[172:175], v[136:139]
	v_mfma_f32_16x16x32_bf16 v[124:127], v[96:99], v[190:193], v[124:127]
	v_mfma_f32_16x16x32_bf16 v[120:123], v[104:107], v[190:193], v[120:123]
	v_mfma_f32_16x16x32_bf16 v[92:95], v[96:99], v[198:201], v[92:95]
	v_mfma_f32_16x16x32_bf16 v[88:91], v[104:107], v[198:201], v[88:91]
	v_mfma_f32_16x16x32_bf16 v[76:79], v[96:99], v[206:209], v[76:79]
	v_mfma_f32_16x16x32_bf16 v[72:75], v[104:107], v[206:209], v[72:75]
	v_mfma_f32_16x16x32_bf16 v[140:143], v[100:103], v[176:179], v[140:143]
	v_mfma_f32_16x16x32_bf16 v[136:139], v[108:111], v[176:179], v[136:139]
	v_mfma_f32_16x16x32_bf16 v[124:127], v[100:103], v[194:197], v[124:127]
	v_mfma_f32_16x16x32_bf16 v[120:123], v[108:111], v[194:197], v[120:123]
	v_mfma_f32_16x16x32_bf16 v[92:95], v[100:103], v[202:205], v[92:95]
	v_mfma_f32_16x16x32_bf16 v[88:91], v[108:111], v[202:205], v[88:91]
	v_mfma_f32_16x16x32_bf16 v[76:79], v[100:103], v[212:215], v[76:79]
	v_mfma_f32_16x16x32_bf16 v[72:75], v[108:111], v[212:215], v[72:75]
	v_mfma_f32_16x16x32_bf16 v[132:135], v[156:159], v[172:175], v[132:135]
	v_mfma_f32_16x16x32_bf16 v[128:131], v[164:167], v[172:175], v[128:131]
	v_mfma_f32_16x16x32_bf16 v[116:119], v[156:159], v[190:193], v[116:119]
	v_mfma_f32_16x16x32_bf16 v[112:115], v[164:167], v[190:193], v[112:115]
	v_mfma_f32_16x16x32_bf16 v[84:87], v[156:159], v[198:201], v[84:87]
	v_mfma_f32_16x16x32_bf16 v[80:83], v[164:167], v[198:201], v[80:83]
	v_mfma_f32_16x16x32_bf16 v[68:71], v[156:159], v[206:209], v[68:71]
	v_mfma_f32_16x16x32_bf16 v[64:67], v[164:167], v[206:209], v[64:67]
	v_mfma_f32_16x16x32_bf16 v[132:135], v[160:163], v[176:179], v[132:135]
	v_mfma_f32_16x16x32_bf16 v[128:131], v[168:171], v[176:179], v[128:131]
	v_mfma_f32_16x16x32_bf16 v[116:119], v[160:163], v[194:197], v[116:119]
	v_mfma_f32_16x16x32_bf16 v[112:115], v[168:171], v[194:197], v[112:115]
	v_mfma_f32_16x16x32_bf16 v[84:87], v[160:163], v[202:205], v[84:87]
	v_mfma_f32_16x16x32_bf16 v[80:83], v[168:171], v[202:205], v[80:83]
	v_mfma_f32_16x16x32_bf16 v[68:71], v[160:163], v[212:215], v[68:71]
	v_mfma_f32_16x16x32_bf16 v[64:67], v[168:171], v[212:215], v[64:67]
	s_setprio 0
	s_barrier
	s_add_i32 s26, s58, s3
	v_lshl_add_u64 v[180:181], v[180:181], 0, s[16:17]
	s_mov_b32 m0, s26
	ds_read_b128 v[172:175], v187 offset:49152
	ds_read_b128 v[176:179], v187 offset:50176
	ds_read_b128 v[190:193], v187 offset:51200
	ds_read_b128 v[194:197], v187 offset:52224
	ds_read_b128 v[198:201], v187 offset:53248
	ds_read_b128 v[202:205], v187 offset:54272
	ds_read_b128 v[206:209], v187 offset:55296
	ds_read_b128 v[212:215], v187 offset:56320
	global_load_lds_dwordx4 v[180:181], off
	s_add_i32 m0, s26, 0x2000
	s_add_u32 s26, s34, 0xb0080
	v_lshl_add_u64 v[180:181], v[216:217], 0, s[16:17]
	s_addc_u32 s27, s35, 0
	s_add_i32 s34, s59, s3
	global_load_lds_dwordx4 v[180:181], off
	v_lshl_add_u64 v[180:181], s[26:27], 0, v[144:145]
	s_mov_b32 m0, s34
	s_nop 0
	global_load_lds_dwordx4 v[180:181], off
	v_lshl_add_u64 v[180:181], s[26:27], 0, v[146:147]
	s_add_i32 m0, s34, 0x2000
	s_nop 0
	global_load_lds_dwordx4 v[180:181], off
	v_lshl_add_u64 v[180:181], v[218:219], 0, s[16:17]
	s_mov_b32 m0, s45
	s_nop 0
	global_load_lds_dwordx4 v[180:181], off
	v_lshl_add_u64 v[180:181], v[220:221], 0, s[16:17]
	s_mov_b32 m0, s46
	s_nop 0
	global_load_lds_dwordx4 v[180:181], off
	s_waitcnt vmcnt(6)
	s_waitcnt lgkmcnt(0)
	s_barrier
	s_setprio 1
	s_waitcnt lgkmcnt(0)
	v_mfma_f32_16x16x32_bf16 v[60:63], v[96:99], v[172:175], v[60:63]
	v_mfma_f32_16x16x32_bf16 v[56:59], v[104:107], v[172:175], v[56:59]
	v_mfma_f32_16x16x32_bf16 v[44:47], v[96:99], v[190:193], v[44:47]
	v_mfma_f32_16x16x32_bf16 v[40:43], v[104:107], v[190:193], v[40:43]
	v_mfma_f32_16x16x32_bf16 v[28:31], v[96:99], v[198:201], v[28:31]
	v_mfma_f32_16x16x32_bf16 v[24:27], v[104:107], v[198:201], v[24:27]
	v_mfma_f32_16x16x32_bf16 v[12:15], v[96:99], v[206:209], v[12:15]
	v_mfma_f32_16x16x32_bf16 v[8:11], v[104:107], v[206:209], v[8:11]
	v_mfma_f32_16x16x32_bf16 v[60:63], v[100:103], v[176:179], v[60:63]
	v_mfma_f32_16x16x32_bf16 v[56:59], v[108:111], v[176:179], v[56:59]
	v_mfma_f32_16x16x32_bf16 v[44:47], v[100:103], v[194:197], v[44:47]
	v_mfma_f32_16x16x32_bf16 v[40:43], v[108:111], v[194:197], v[40:43]
	v_mfma_f32_16x16x32_bf16 v[28:31], v[100:103], v[202:205], v[28:31]
	v_mfma_f32_16x16x32_bf16 v[24:27], v[108:111], v[202:205], v[24:27]
	v_mfma_f32_16x16x32_bf16 v[12:15], v[100:103], v[212:215], v[12:15]
	v_mfma_f32_16x16x32_bf16 v[8:11], v[108:111], v[212:215], v[8:11]
	v_mfma_f32_16x16x32_bf16 v[52:55], v[156:159], v[172:175], v[52:55]
	v_mfma_f32_16x16x32_bf16 v[48:51], v[164:167], v[172:175], v[48:51]
	v_mfma_f32_16x16x32_bf16 v[36:39], v[156:159], v[190:193], v[36:39]
	v_mfma_f32_16x16x32_bf16 v[32:35], v[164:167], v[190:193], v[32:35]
	v_mfma_f32_16x16x32_bf16 v[20:23], v[156:159], v[198:201], v[20:23]
	v_mfma_f32_16x16x32_bf16 v[16:19], v[164:167], v[198:201], v[16:19]
	v_mfma_f32_16x16x32_bf16 v[4:7], v[156:159], v[206:209], v[4:7]
	v_mfma_f32_16x16x32_bf16 v[0:3], v[164:167], v[206:209], v[0:3]
	v_mfma_f32_16x16x32_bf16 v[52:55], v[160:163], v[176:179], v[52:55]
	v_mfma_f32_16x16x32_bf16 v[48:51], v[168:171], v[176:179], v[48:51]
	v_mfma_f32_16x16x32_bf16 v[36:39], v[160:163], v[194:197], v[36:39]
	v_mfma_f32_16x16x32_bf16 v[32:35], v[168:171], v[194:197], v[32:35]
	v_mfma_f32_16x16x32_bf16 v[20:23], v[160:163], v[202:205], v[20:23]
	v_mfma_f32_16x16x32_bf16 v[16:19], v[168:171], v[202:205], v[16:19]
	v_mfma_f32_16x16x32_bf16 v[4:7], v[160:163], v[212:215], v[4:7]
	v_mfma_f32_16x16x32_bf16 v[0:3], v[168:171], v[212:215], v[0:3]
	s_setprio 0
	s_barrier
	s_add_i32 s57, s57, 2
	s_add_u32 s55, s55, 0x100
	s_addc_u32 s56, s56, 0
	s_cmp_gt_u32 s57, 41
	s_mov_b64 s[26:27], s[28:29]
	s_cbranch_scc0 .LBB0_722
	s_and_b64 vcc, exec, s[20:21]
	s_cbranch_vccz .LBB0_725
	s_barrier
